# LN epilogues: touch (dword loads to a dead VGPR) the x lines of load groups 2 and 3 right after group 1 so the later loads hit L2; first wait vmcnt(16)
# baseline (speedup 1.0000x reference)
.LBB0_239:
	s_waitcnt lgkmcnt(0)
	v_readlane_b32 s2, v254, 27
	s_mul_i32 s2, s2, 0xb4000
	v_readlane_b32 s3, v254, 28
	s_add_u32 s2, s22, s2
	s_addc_u32 s3, s23, 0
	s_add_u32 s59, s2, 0x100000
	s_addc_u32 s67, s3, 0
	s_lshr_b32 s2, s72, 14
	s_add_i32 s18, s2, 8
	s_ashr_i32 s19, s53, 4
	s_and_b64 s[2:3], s[56:57], exec
	s_cselect_b32 s2, s18, s19
	s_mul_hi_i32 s3, s2, 0x4800
	s_mulk_i32 s2, 0x4800
	s_lshl_b32 s69, s82, 8
	s_lshl_b64 s[18:19], s[2:3], 2
	v_or_b32_e32 v132, s69, v177
	s_add_u32 s2, s59, s18
	s_addc_u32 s3, s67, s19
	v_ashrrev_i32_e32 v133, 31, v132
	v_lshl_add_u64 v[132:133], v[132:133], 2, s[2:3]
	s_mov_b64 s[2:3], 0x4000
	v_or_b32_e32 v148, v179, v178
	v_lshl_add_u64 v[144:145], v[132:133], 0, s[2:3]
	s_movk_i32 s2, 0x4000
	v_add_u32_e32 v148, s69, v148
	v_add_co_u32_e32 v140, vcc, s2, v132
	v_ashrrev_i32_e32 v149, 31, v148
	v_readlane_b32 s2, v254, 48
	v_lshl_add_u64 v[152:153], v[148:149], 2, s[14:15]
	v_readlane_b32 s3, v254, 49
	v_addc_co_u32_e32 v141, vcc, 0, v133, vcc
	v_lshl_add_u64 v[154:155], v[152:153], 0, s[28:29]
	v_lshl_add_u64 v[162:163], v[152:153], 0, s[2:3]
	v_readlane_b32 s2, v254, 52
	global_load_dwordx4 v[132:135], v[144:145], off offset:64
	global_load_dwordx4 v[136:139], v[144:145], off offset:512
	s_nop 0
	global_load_dwordx4 v[140:143], v[140:141], off
	s_nop 0
	global_load_dwordx4 v[144:147], v[144:145], off offset:576
	s_nop 0
	global_load_dwordx4 v[148:151], v[154:155], off nt
	s_nop 0
	global_load_dwordx4 v[154:157], v[154:155], off offset:512 nt
	s_nop 0
	global_load_dwordx4 v[158:161], v[162:163], off nt
	global_load_dwordx4 v[170:173], v[162:163], off offset:512 nt
	v_lshl_add_u64 v[162:163], v[152:153], 0, s[36:37]
	v_readlane_b32 s3, v254, 53
	global_load_dwordx4 v[186:189], v[162:163], off nt
	global_load_dwordx4 v[190:193], v[162:163], off offset:512 nt
	v_lshl_add_u64 v[162:163], v[152:153], 0, s[2:3]
	v_readlane_b32 s2, v254, 56
	global_load_dwordx4 v[194:197], v[162:163], off nt
	global_load_dwordx4 v[198:201], v[162:163], off offset:512 nt
	v_lshl_add_u64 v[162:163], v[152:153], 0, s[42:43]
	v_readlane_b32 s3, v254, 57
	global_load_dwordx4 v[202:205], v[162:163], off nt
	global_load_dwordx4 v[214:217], v[162:163], off offset:512 nt
	v_lshl_add_u64 v[162:163], v[152:153], 0, s[2:3]
	v_readlane_b32 s2, v254, 60
	global_load_dwordx4 v[218:221], v[162:163], off nt
	global_load_dwordx4 v[222:225], v[162:163], off offset:512 nt
	v_lshl_add_u64 v[162:163], v[152:153], 0, s[48:49]
	v_readlane_b32 s3, v254, 61
	global_load_dwordx4 v[226:229], v[162:163], off nt
	global_load_dwordx4 v[230:233], v[162:163], off offset:512 nt
	v_lshl_add_u64 v[162:163], v[152:153], 0, s[2:3]
	global_load_dwordx4 v[234:237], v[162:163], off nt
	global_load_dwordx4 v[238:241], v[162:163], off offset:512 nt
	v_lshl_add_u64 v[162:163], v[152:153], 0, s[54:55]
	global_load_dword v250, v[162:163], off
	global_load_dword v250, v[162:163], off offset:512
	v_readlane_b32 s2, v255, 0
	v_readlane_b32 s3, v255, 1
	s_nop 1
	v_lshl_add_u64 v[162:163], v[152:153], 0, s[2:3]
	global_load_dword v250, v[162:163], off
	global_load_dword v250, v[162:163], off offset:512
	v_lshl_add_u64 v[162:163], v[152:153], 0, s[60:61]
	global_load_dword v250, v[162:163], off
	global_load_dword v250, v[162:163], off offset:512
	v_readlane_b32 s2, v255, 2
	v_readlane_b32 s3, v255, 3
	s_nop 1
	v_lshl_add_u64 v[162:163], v[152:153], 0, s[2:3]
	global_load_dword v250, v[162:163], off
	global_load_dword v250, v[162:163], off offset:512
	v_lshl_add_u64 v[162:163], v[152:153], 0, s[70:71]
	global_load_dword v250, v[162:163], off
	global_load_dword v250, v[162:163], off offset:512
	v_readlane_b32 s2, v255, 4
	v_readlane_b32 s3, v255, 5
	s_nop 1
	v_lshl_add_u64 v[162:163], v[152:153], 0, s[2:3]
	global_load_dword v250, v[162:163], off
	global_load_dword v250, v[162:163], off offset:512
	v_lshl_add_u64 v[162:163], v[152:153], 0, s[96:97]
	global_load_dword v250, v[162:163], off
	global_load_dword v250, v[162:163], off offset:512
	v_readlane_b32 s2, v255, 6
	v_readlane_b32 s3, v255, 7
	s_nop 1
	v_lshl_add_u64 v[162:163], v[152:153], 0, s[2:3]
	global_load_dword v250, v[162:163], off
	global_load_dword v250, v[162:163], off offset:512
	s_waitcnt vmcnt(16)
	ds_write_b128 v176, v[148:151]
	ds_write_b128 v176, v[158:161] offset:1152
	ds_read_b128 v[148:151], v175
	ds_read_b128 v[158:161], v175 offset:64
	ds_write_b128 v176, v[154:157]
	ds_write_b128 v176, v[170:173] offset:1152
	ds_read_b128 v[154:157], v175
	ds_read_b128 v[170:173], v175 offset:64
	v_pk_add_f32 v[142:143], v[142:143], 1.0 op_sel_hi:[1,0]
	v_pk_add_f32 v[162:163], v[140:141], 1.0 op_sel_hi:[1,0]
	ds_write_b128 v176, v[186:189]
	ds_write_b128 v176, v[194:197] offset:1152
	v_pk_mul_f32 v[140:141], v[142:143], 0.5 op_sel_hi:[1,0]
	v_pk_mul_f32 v[142:143], v[162:163], 0.5 op_sel_hi:[1,0]
	s_waitcnt lgkmcnt(6)
	v_pk_mul_f32 v[162:163], v[160:161], s[80:81] op_sel_hi:[1,0]
	v_pk_mul_f32 v[206:207], v[158:159], s[80:81] op_sel_hi:[1,0]
	ds_read_b128 v[158:161], v175
	ds_read_b128 v[186:189], v175 offset:64
	v_pk_mul_f32 v[150:151], v[150:151], s[80:81] op_sel_hi:[1,0]
	v_pk_mul_f32 v[148:149], v[148:149], s[80:81] op_sel_hi:[1,0]
	v_pk_add_f32 v[134:135], v[134:135], 1.0 op_sel_hi:[1,0]
	v_pk_add_f32 v[132:133], v[132:133], 1.0 op_sel_hi:[1,0]
	v_pk_fma_f32 v[130:131], v[130:131], v[140:141], v[150:151]
	v_pk_fma_f32 v[128:129], v[128:129], v[142:143], v[148:149]
	v_pk_mul_f32 v[148:149], v[134:135], 0.5 op_sel_hi:[1,0]
	v_pk_mul_f32 v[150:151], v[132:133], 0.5 op_sel_hi:[1,0]
	v_pk_fma_f32 v[134:135], v[126:127], v[148:149], v[162:163]
	v_pk_fma_f32 v[132:133], v[124:125], v[150:151], v[206:207]
	v_pk_add_f32 v[124:125], v[138:139], 1.0 op_sel_hi:[1,0]
	v_pk_add_f32 v[126:127], v[136:137], 1.0 op_sel_hi:[1,0]
	s_waitcnt lgkmcnt(5)
	v_pk_mul_f32 v[156:157], v[156:157], s[80:81] op_sel_hi:[1,0]
	v_pk_mul_f32 v[154:155], v[154:155], s[80:81] op_sel_hi:[1,0]
	v_pk_mul_f32 v[124:125], v[124:125], 0.5 op_sel_hi:[1,0]
	v_pk_mul_f32 v[126:127], v[126:127], 0.5 op_sel_hi:[1,0]
	ds_write_b128 v176, v[190:193]
	ds_write_b128 v176, v[198:201] offset:1152
	v_pk_fma_f32 v[138:139], v[122:123], v[124:125], v[156:157]
	v_pk_fma_f32 v[136:137], v[120:121], v[126:127], v[154:155]
	s_waitcnt lgkmcnt(6)
	v_pk_mul_f32 v[162:163], v[172:173], s[80:81] op_sel_hi:[1,0]
	v_pk_mul_f32 v[194:195], v[170:171], s[80:81] op_sel_hi:[1,0]
	ds_read_b128 v[154:157], v175
	ds_read_b128 v[170:173], v175 offset:64
	v_pk_add_f32 v[120:121], v[146:147], 1.0 op_sel_hi:[1,0]
	v_pk_add_f32 v[122:123], v[144:145], 1.0 op_sel_hi:[1,0]
	v_pk_mul_f32 v[120:121], v[120:121], 0.5 op_sel_hi:[1,0]
	v_pk_mul_f32 v[122:123], v[122:123], 0.5 op_sel_hi:[1,0]
	v_pk_fma_f32 v[146:147], v[106:107], v[120:121], v[162:163]
	v_pk_fma_f32 v[144:145], v[104:105], v[122:123], v[194:195]
	s_waitcnt lgkmcnt(5)
	v_pk_mul_f32 v[104:105], v[160:161], s[80:81] op_sel_hi:[1,0]
	v_pk_mul_f32 v[106:107], v[158:159], s[80:81] op_sel_hi:[1,0]
	v_pk_fma_f32 v[110:111], v[110:111], v[140:141], v[104:105]
	v_pk_fma_f32 v[108:109], v[108:109], v[142:143], v[106:107]
	s_waitcnt lgkmcnt(4)
	v_pk_mul_f32 v[104:105], v[188:189], s[80:81] op_sel_hi:[1,0]
	v_pk_mul_f32 v[106:107], v[186:187], s[80:81] op_sel_hi:[1,0]
	v_pk_fma_f32 v[118:119], v[118:119], v[148:149], v[104:105]
	v_pk_fma_f32 v[116:117], v[116:117], v[150:151], v[106:107]
	s_waitcnt lgkmcnt(1)
	v_pk_mul_f32 v[104:105], v[156:157], s[80:81] op_sel_hi:[1,0]
	v_pk_mul_f32 v[106:107], v[154:155], s[80:81] op_sel_hi:[1,0]
	v_pk_fma_f32 v[102:103], v[102:103], v[124:125], v[104:105]
	s_waitcnt lgkmcnt(0)
	v_pk_mul_f32 v[104:105], v[172:173], s[80:81] op_sel_hi:[1,0]
	v_pk_mul_f32 v[154:155], v[170:171], s[80:81] op_sel_hi:[1,0]
	v_pk_fma_f32 v[100:101], v[100:101], v[126:127], v[106:107]
	v_pk_fma_f32 v[106:107], v[98:99], v[120:121], v[104:105]
	v_pk_fma_f32 v[104:105], v[96:97], v[122:123], v[154:155]
	v_readlane_b32 s2, v255, 0
	v_lshl_add_u64 v[96:97], v[152:153], 0, s[54:55]
	v_readlane_b32 s3, v255, 1
	global_load_dwordx4 v[154:157], v[96:97], off nt
	global_load_dwordx4 v[158:161], v[96:97], off offset:512 nt
	v_lshl_add_u64 v[96:97], v[152:153], 0, s[2:3]
	v_readlane_b32 s2, v255, 2
	global_load_dwordx4 v[170:173], v[96:97], off nt
	global_load_dwordx4 v[186:189], v[96:97], off offset:512 nt
	v_lshl_add_u64 v[96:97], v[152:153], 0, s[60:61]
	v_readlane_b32 s3, v255, 3
	global_load_dwordx4 v[190:193], v[96:97], off nt
	global_load_dwordx4 v[194:197], v[96:97], off offset:512 nt
	v_lshl_add_u64 v[96:97], v[152:153], 0, s[2:3]
	global_load_dwordx4 v[198:201], v[96:97], off nt
	global_load_dwordx4 v[250:253], v[96:97], off offset:512 nt
	ds_write_b128 v176, v[202:205]
	ds_write_b128 v176, v[218:221] offset:1152
	ds_read_b128 v[96:99], v175
	ds_read_b128 v[202:205], v175 offset:64
	ds_write_b128 v176, v[214:217]
	ds_write_b128 v176, v[222:225] offset:1152
	ds_read_b128 v[214:217], v175
	ds_read_b128 v[218:221], v175 offset:64
	ds_write_b128 v176, v[226:229]
	ds_write_b128 v176, v[234:237] offset:1152
	ds_read_b128 v[222:225], v175
	ds_read_b128 v[226:229], v175 offset:64
	s_waitcnt lgkmcnt(9)
	v_pk_mul_f32 v[96:97], v[96:97], s[80:81] op_sel_hi:[1,0]
	v_pk_mul_f32 v[98:99], v[98:99], s[80:81] op_sel_hi:[1,0]
	v_pk_fma_f32 v[92:93], v[92:93], v[142:143], v[96:97]
	s_waitcnt lgkmcnt(8)
	v_pk_mul_f32 v[96:97], v[204:205], s[80:81] op_sel_hi:[1,0]
	v_pk_mul_f32 v[162:163], v[202:203], s[80:81] op_sel_hi:[1,0]
	v_pk_fma_f32 v[94:95], v[94:95], v[140:141], v[98:99]
	v_pk_fma_f32 v[98:99], v[90:91], v[148:149], v[96:97]
	v_pk_fma_f32 v[96:97], v[88:89], v[150:151], v[162:163]
	ds_write_b128 v176, v[230:233]
	ds_write_b128 v176, v[238:241] offset:1152
	s_waitcnt lgkmcnt(7)
	v_pk_mul_f32 v[88:89], v[216:217], s[80:81] op_sel_hi:[1,0]
	v_pk_mul_f32 v[90:91], v[214:215], s[80:81] op_sel_hi:[1,0]
	ds_read_b128 v[202:205], v175
	ds_read_b128 v[214:217], v175 offset:64
	v_pk_fma_f32 v[86:87], v[86:87], v[124:125], v[88:89]
	s_waitcnt lgkmcnt(8)
	v_pk_mul_f32 v[88:89], v[220:221], s[80:81] op_sel_hi:[1,0]
	v_pk_mul_f32 v[162:163], v[218:219], s[80:81] op_sel_hi:[1,0]
	v_pk_fma_f32 v[84:85], v[84:85], v[126:127], v[90:91]
	v_pk_fma_f32 v[90:91], v[74:75], v[120:121], v[88:89]
	v_pk_fma_f32 v[88:89], v[72:73], v[122:123], v[162:163]
	s_waitcnt lgkmcnt(5)
	v_pk_mul_f32 v[72:73], v[224:225], s[80:81] op_sel_hi:[1,0]
	v_pk_mul_f32 v[74:75], v[222:223], s[80:81] op_sel_hi:[1,0]
	v_pk_fma_f32 v[78:79], v[78:79], v[140:141], v[72:73]
	v_pk_fma_f32 v[76:77], v[76:77], v[142:143], v[74:75]
	s_waitcnt lgkmcnt(4)
	v_pk_mul_f32 v[72:73], v[228:229], s[80:81] op_sel_hi:[1,0]
	v_pk_mul_f32 v[74:75], v[226:227], s[80:81] op_sel_hi:[1,0]
	v_pk_fma_f32 v[82:83], v[82:83], v[148:149], v[72:73]
	v_pk_fma_f32 v[80:81], v[80:81], v[150:151], v[74:75]
	s_waitcnt lgkmcnt(1)
	v_pk_mul_f32 v[72:73], v[204:205], s[80:81] op_sel_hi:[1,0]
	v_pk_mul_f32 v[74:75], v[202:203], s[80:81] op_sel_hi:[1,0]
	v_pk_fma_f32 v[70:71], v[70:71], v[124:125], v[72:73]
	s_waitcnt lgkmcnt(0)
	v_pk_mul_f32 v[72:73], v[216:217], s[80:81] op_sel_hi:[1,0]
	v_pk_mul_f32 v[162:163], v[214:215], s[80:81] op_sel_hi:[1,0]
	v_pk_fma_f32 v[68:69], v[68:69], v[126:127], v[74:75]
	v_pk_fma_f32 v[74:75], v[66:67], v[120:121], v[72:73]
	v_pk_fma_f32 v[72:73], v[64:65], v[122:123], v[162:163]
	v_readlane_b32 s2, v255, 4
	v_lshl_add_u64 v[64:65], v[152:153], 0, s[70:71]
	v_readlane_b32 s3, v255, 5
	global_load_dwordx4 v[202:205], v[64:65], off nt
	global_load_dwordx4 v[214:217], v[64:65], off offset:512 nt
	v_lshl_add_u64 v[64:65], v[152:153], 0, s[2:3]
	v_readlane_b32 s2, v255, 6
	global_load_dwordx4 v[218:221], v[64:65], off nt
	global_load_dwordx4 v[222:225], v[64:65], off offset:512 nt
	v_lshl_add_u64 v[64:65], v[152:153], 0, s[96:97]
	v_readlane_b32 s3, v255, 7
	global_load_dwordx4 v[226:229], v[64:65], off nt
	global_load_dwordx4 v[230:233], v[64:65], off offset:512 nt
	v_lshl_add_u64 v[64:65], v[152:153], 0, s[2:3]
	global_load_dwordx4 v[234:237], v[64:65], off nt
	global_load_dwordx4 v[238:241], v[64:65], off offset:512 nt
	s_waitcnt vmcnt(15)
	ds_write_b128 v176, v[154:157]
	s_waitcnt vmcnt(13)
	ds_write_b128 v176, v[170:173] offset:1152
	ds_read_b128 v[64:67], v175
	ds_read_b128 v[152:155], v175 offset:64
	ds_write_b128 v176, v[158:161]
	s_waitcnt vmcnt(12)
	ds_write_b128 v176, v[186:189] offset:1152
	ds_read_b128 v[156:159], v175
	ds_read_b128 v[160:163], v175 offset:64
	s_waitcnt vmcnt(11)
	ds_write_b128 v176, v[190:193]
	s_waitcnt vmcnt(9)
	ds_write_b128 v176, v[198:201] offset:1152
	ds_read_b128 v[170:173], v175
	ds_read_b128 v[186:189], v175 offset:64
	s_waitcnt lgkmcnt(9)
	v_pk_mul_f32 v[64:65], v[64:65], s[80:81] op_sel_hi:[1,0]
	v_pk_mul_f32 v[66:67], v[66:67], s[80:81] op_sel_hi:[1,0]
	v_pk_fma_f32 v[60:61], v[60:61], v[142:143], v[64:65]
	s_waitcnt lgkmcnt(8)
	v_pk_mul_f32 v[64:65], v[154:155], s[80:81] op_sel_hi:[1,0]
	v_pk_mul_f32 v[152:153], v[152:153], s[80:81] op_sel_hi:[1,0]
	v_pk_fma_f32 v[62:63], v[62:63], v[140:141], v[66:67]
	v_pk_fma_f32 v[66:67], v[58:59], v[148:149], v[64:65]
	v_pk_fma_f32 v[64:65], v[56:57], v[150:151], v[152:153]
	ds_write_b128 v176, v[194:197]
	s_waitcnt vmcnt(8)
	ds_write_b128 v176, v[250:253] offset:1152
	s_waitcnt lgkmcnt(7)
	v_pk_mul_f32 v[56:57], v[158:159], s[80:81] op_sel_hi:[1,0]
	v_pk_mul_f32 v[58:59], v[156:157], s[80:81] op_sel_hi:[1,0]
	ds_read_b128 v[152:155], v175
	ds_read_b128 v[156:159], v175 offset:64
	v_pk_fma_f32 v[54:55], v[54:55], v[124:125], v[56:57]
	s_waitcnt lgkmcnt(8)
	v_pk_mul_f32 v[56:57], v[162:163], s[80:81] op_sel_hi:[1,0]
	v_pk_mul_f32 v[160:161], v[160:161], s[80:81] op_sel_hi:[1,0]
	v_pk_fma_f32 v[52:53], v[52:53], v[126:127], v[58:59]
	v_pk_fma_f32 v[58:59], v[42:43], v[120:121], v[56:57]
	v_pk_fma_f32 v[56:57], v[40:41], v[122:123], v[160:161]
	s_waitcnt lgkmcnt(5)
	v_pk_mul_f32 v[40:41], v[172:173], s[80:81] op_sel_hi:[1,0]
	v_pk_mul_f32 v[42:43], v[170:171], s[80:81] op_sel_hi:[1,0]
	v_pk_fma_f32 v[46:47], v[46:47], v[140:141], v[40:41]
	v_pk_fma_f32 v[44:45], v[44:45], v[142:143], v[42:43]
	s_waitcnt lgkmcnt(4)
	v_pk_mul_f32 v[40:41], v[188:189], s[80:81] op_sel_hi:[1,0]
	v_pk_mul_f32 v[42:43], v[186:187], s[80:81] op_sel_hi:[1,0]
	v_pk_fma_f32 v[50:51], v[50:51], v[148:149], v[40:41]
	v_pk_fma_f32 v[48:49], v[48:49], v[150:151], v[42:43]
	s_waitcnt lgkmcnt(1)
	v_pk_mul_f32 v[40:41], v[154:155], s[80:81] op_sel_hi:[1,0]
	v_pk_mul_f32 v[42:43], v[152:153], s[80:81] op_sel_hi:[1,0]
	v_pk_fma_f32 v[38:39], v[38:39], v[124:125], v[40:41]
	s_waitcnt lgkmcnt(0)
	v_pk_mul_f32 v[40:41], v[158:159], s[80:81] op_sel_hi:[1,0]
	v_pk_mul_f32 v[152:153], v[156:157], s[80:81] op_sel_hi:[1,0]
	v_pk_fma_f32 v[36:37], v[36:37], v[126:127], v[42:43]
	v_pk_fma_f32 v[42:43], v[34:35], v[120:121], v[40:41]
	v_pk_fma_f32 v[40:41], v[32:33], v[122:123], v[152:153]
	s_nop 0
	s_waitcnt vmcnt(7)
	ds_write_b128 v176, v[202:205]
	s_waitcnt vmcnt(5)
	ds_write_b128 v176, v[218:221] offset:1152
	ds_read_b128 v[32:35], v175
	ds_read_b128 v[152:155], v175 offset:64
	ds_write_b128 v176, v[214:217]
	s_waitcnt vmcnt(4)
	ds_write_b128 v176, v[222:225] offset:1152
	ds_read_b128 v[156:159], v175
	ds_read_b128 v[160:163], v175 offset:64
	s_waitcnt vmcnt(3)
	ds_write_b128 v176, v[226:229]
	s_waitcnt vmcnt(1)
	ds_write_b128 v176, v[234:237] offset:1152
	ds_read_b128 v[170:173], v175
	ds_read_b128 v[186:189], v175 offset:64
	s_waitcnt lgkmcnt(9)
	v_pk_mul_f32 v[32:33], v[32:33], s[80:81] op_sel_hi:[1,0]
	v_pk_mul_f32 v[34:35], v[34:35], s[80:81] op_sel_hi:[1,0]
	v_pk_fma_f32 v[28:29], v[28:29], v[142:143], v[32:33]
	s_waitcnt lgkmcnt(8)
	v_pk_mul_f32 v[32:33], v[154:155], s[80:81] op_sel_hi:[1,0]
	v_pk_mul_f32 v[152:153], v[152:153], s[80:81] op_sel_hi:[1,0]
	v_pk_fma_f32 v[30:31], v[30:31], v[140:141], v[34:35]
	v_pk_fma_f32 v[34:35], v[26:27], v[148:149], v[32:33]
	v_pk_fma_f32 v[32:33], v[24:25], v[150:151], v[152:153]
	ds_write_b128 v176, v[230:233]
	s_waitcnt vmcnt(0)
	ds_write_b128 v176, v[238:241] offset:1152
	s_waitcnt lgkmcnt(7)
	v_pk_mul_f32 v[24:25], v[158:159], s[80:81] op_sel_hi:[1,0]
	v_pk_mul_f32 v[26:27], v[156:157], s[80:81] op_sel_hi:[1,0]
	ds_read_b128 v[152:155], v175
	ds_read_b128 v[156:159], v175 offset:64
	v_pk_fma_f32 v[22:23], v[22:23], v[124:125], v[24:25]
	s_waitcnt lgkmcnt(8)
	v_pk_mul_f32 v[24:25], v[162:163], s[80:81] op_sel_hi:[1,0]
	v_pk_mul_f32 v[160:161], v[160:161], s[80:81] op_sel_hi:[1,0]
	v_pk_fma_f32 v[20:21], v[20:21], v[126:127], v[26:27]
	v_pk_fma_f32 v[26:27], v[14:15], v[120:121], v[24:25]
	v_pk_fma_f32 v[24:25], v[12:13], v[122:123], v[160:161]
	s_waitcnt lgkmcnt(5)
	v_pk_mul_f32 v[12:13], v[172:173], s[80:81] op_sel_hi:[1,0]
	v_pk_mul_f32 v[160:161], v[170:171], s[80:81] op_sel_hi:[1,0]
	v_pk_fma_f32 v[14:15], v[114:115], v[140:141], v[12:13]
	v_pk_fma_f32 v[12:13], v[112:113], v[142:143], v[160:161]
	s_waitcnt lgkmcnt(4)
	v_pk_mul_f32 v[112:113], v[188:189], s[80:81] op_sel_hi:[1,0]
	v_pk_mul_f32 v[114:115], v[186:187], s[80:81] op_sel_hi:[1,0]
	v_pk_fma_f32 v[18:19], v[18:19], v[148:149], v[112:113]
	v_pk_fma_f32 v[16:17], v[16:17], v[150:151], v[114:115]
	s_waitcnt lgkmcnt(1)
	v_pk_mul_f32 v[112:113], v[154:155], s[80:81] op_sel_hi:[1,0]
	v_pk_mul_f32 v[114:115], v[152:153], s[80:81] op_sel_hi:[1,0]
	v_pk_fma_f32 v[6:7], v[6:7], v[124:125], v[112:113]
	s_waitcnt lgkmcnt(0)
	v_pk_mul_f32 v[112:113], v[158:159], s[80:81] op_sel_hi:[1,0]
	v_pk_fma_f32 v[4:5], v[4:5], v[126:127], v[114:115]
	v_pk_mul_f32 v[114:115], v[156:157], s[80:81] op_sel_hi:[1,0]
	v_pk_fma_f32 v[10:11], v[10:11], v[120:121], v[112:113]
	v_add_f32_e32 v112, v128, v129
	v_add_f32_e32 v113, v130, v131
	v_pk_fma_f32 v[8:9], v[8:9], v[122:123], v[114:115]
	v_add_f32_e32 v112, v112, v113
	v_mul_f32_e32 v113, v129, v129
	v_mul_f32_e32 v114, v131, v131
	v_fmac_f32_e32 v113, v128, v128
	v_fmac_f32_e32 v114, v130, v130
	v_add_f32_e32 v113, v113, v114
	v_add_f32_e32 v114, v132, v133
	v_add_f32_e32 v115, v134, v135
	v_add_f32_e32 v112, 0, v112
	v_add_f32_e32 v114, v114, v115
	v_add_f32_e32 v112, v114, v112
	v_mul_f32_e32 v114, v133, v133
	v_mul_f32_e32 v115, v135, v135
	v_fmac_f32_e32 v114, v132, v132
	v_fmac_f32_e32 v115, v134, v134
	v_add_f32_e32 v114, v114, v115
	v_add_f32_e32 v113, v113, v114
	v_add_f32_e32 v114, v136, v137
	v_add_f32_e32 v115, v138, v139
	v_add_f32_e32 v114, v114, v115
	v_add_f32_e32 v112, v114, v112
	v_mul_f32_e32 v114, v137, v137
	v_mul_f32_e32 v115, v139, v139
	v_fmac_f32_e32 v114, v136, v136
	v_fmac_f32_e32 v115, v138, v138
	v_add_f32_e32 v114, v114, v115
	v_add_f32_e32 v113, v114, v113
	v_add_f32_e32 v114, v144, v145
	v_add_f32_e32 v115, v146, v147
	v_add_f32_e32 v114, v114, v115
	v_add_f32_e32 v112, v114, v112
	v_mul_f32_e32 v114, v145, v145
	v_mul_f32_e32 v115, v147, v147
	v_fmac_f32_e32 v114, v144, v144
	v_fmac_f32_e32 v115, v146, v146
	v_add_f32_e32 v114, v114, v115
	v_add_f32_e32 v113, v114, v113
	v_mov_b32_e32 v114, v112
	v_mov_b32_e32 v115, v113
	s_nop 0
	v_permlane16_swap_b32_e32 v112, v114
	v_permlane16_swap_b32_e32 v113, v115
	v_add_f32_e32 v112, v112, v114
	v_add_f32_e32 v113, v113, v115
	v_mov_b32_e32 v114, v112
	v_mov_b32_e32 v115, v113
	s_nop 0
	v_permlane32_swap_b32_e32 v112, v114
	v_permlane32_swap_b32_e32 v113, v115
	s_and_saveexec_b64 s[2:3], s[8:9]
	v_pk_add_f32 v[112:113], v[112:113], v[114:115]
	ds_write_b64 v184, v[112:113]
	s_or_b64 exec, exec, s[2:3]
	v_add_f32_e32 v112, v108, v109
	v_add_f32_e32 v113, v110, v111
	v_add_f32_e32 v112, v112, v113
	v_mul_f32_e32 v113, v109, v109
	v_mul_f32_e32 v114, v111, v111
	v_fmac_f32_e32 v113, v108, v108
	v_fmac_f32_e32 v114, v110, v110
	v_add_f32_e32 v113, v113, v114
	v_add_f32_e32 v114, v116, v117
	v_add_f32_e32 v115, v118, v119
	v_add_f32_e32 v112, 0, v112
	v_add_f32_e32 v114, v114, v115
	v_add_f32_e32 v112, v114, v112
	v_mul_f32_e32 v114, v117, v117
	v_mul_f32_e32 v115, v119, v119
	v_fmac_f32_e32 v114, v116, v116
	v_fmac_f32_e32 v115, v118, v118
	v_add_f32_e32 v114, v114, v115
	v_add_f32_e32 v113, v113, v114
	v_add_f32_e32 v114, v100, v101
	v_add_f32_e32 v115, v102, v103
	v_add_f32_e32 v114, v114, v115
	v_add_f32_e32 v112, v114, v112
	v_mul_f32_e32 v114, v101, v101
	v_mul_f32_e32 v115, v103, v103
	v_fmac_f32_e32 v114, v100, v100
	v_fmac_f32_e32 v115, v102, v102
	v_add_f32_e32 v114, v114, v115
	v_add_f32_e32 v113, v114, v113
	v_add_f32_e32 v114, v104, v105
	v_add_f32_e32 v115, v106, v107
	v_add_f32_e32 v114, v114, v115
	v_add_f32_e32 v112, v114, v112
	v_mul_f32_e32 v114, v105, v105
	v_mul_f32_e32 v115, v107, v107
	v_fmac_f32_e32 v114, v104, v104
	v_fmac_f32_e32 v115, v106, v106
	v_add_f32_e32 v114, v114, v115
	v_add_f32_e32 v113, v114, v113
	v_mov_b32_e32 v114, v112
	v_mov_b32_e32 v115, v113
	s_nop 0
	v_permlane16_swap_b32_e32 v112, v114
	v_permlane16_swap_b32_e32 v113, v115
	v_add_f32_e32 v112, v112, v114
	v_add_f32_e32 v113, v113, v115
	v_mov_b32_e32 v114, v112
	v_mov_b32_e32 v115, v113
	s_nop 0
	v_permlane32_swap_b32_e32 v112, v114
	v_permlane32_swap_b32_e32 v113, v115
	s_and_saveexec_b64 s[2:3], s[8:9]
	v_pk_add_f32 v[112:113], v[112:113], v[114:115]
	ds_write_b64 v184, v[112:113] offset:512
	s_or_b64 exec, exec, s[2:3]
	v_add_f32_e32 v112, v92, v93
	v_add_f32_e32 v113, v94, v95
	v_add_f32_e32 v112, v112, v113
	v_mul_f32_e32 v113, v93, v93
	v_mul_f32_e32 v114, v95, v95
	v_fmac_f32_e32 v113, v92, v92
	v_fmac_f32_e32 v114, v94, v94
	v_add_f32_e32 v113, v113, v114
	v_add_f32_e32 v114, v96, v97
	v_add_f32_e32 v115, v98, v99
	v_add_f32_e32 v112, 0, v112
	v_add_f32_e32 v114, v114, v115
	v_add_f32_e32 v112, v114, v112
	v_mul_f32_e32 v114, v97, v97
	v_mul_f32_e32 v115, v99, v99
	v_fmac_f32_e32 v114, v96, v96
	v_fmac_f32_e32 v115, v98, v98
	v_add_f32_e32 v114, v114, v115
	v_add_f32_e32 v113, v113, v114
	v_add_f32_e32 v114, v84, v85
	v_add_f32_e32 v115, v86, v87
	v_add_f32_e32 v114, v114, v115
	v_add_f32_e32 v112, v114, v112
	v_mul_f32_e32 v114, v85, v85
	v_mul_f32_e32 v115, v87, v87
	v_fmac_f32_e32 v114, v84, v84
	v_fmac_f32_e32 v115, v86, v86
	v_add_f32_e32 v114, v114, v115
	v_add_f32_e32 v113, v114, v113
	v_add_f32_e32 v114, v88, v89
	v_add_f32_e32 v115, v90, v91
	v_add_f32_e32 v114, v114, v115
	v_add_f32_e32 v112, v114, v112
	v_mul_f32_e32 v114, v89, v89
	v_mul_f32_e32 v115, v91, v91
	v_fmac_f32_e32 v114, v88, v88
	v_fmac_f32_e32 v115, v90, v90
	v_add_f32_e32 v114, v114, v115
	v_add_f32_e32 v113, v114, v113
	v_mov_b32_e32 v114, v112
	v_mov_b32_e32 v115, v113
	s_nop 0
	v_permlane16_swap_b32_e32 v112, v114
	v_permlane16_swap_b32_e32 v113, v115
	v_add_f32_e32 v112, v112, v114
	v_add_f32_e32 v113, v113, v115
	v_mov_b32_e32 v114, v112
	v_mov_b32_e32 v115, v113
	s_nop 0
	v_permlane32_swap_b32_e32 v112, v114
	v_permlane32_swap_b32_e32 v113, v115
	s_and_saveexec_b64 s[2:3], s[8:9]
	v_pk_add_f32 v[112:113], v[112:113], v[114:115]
	ds_write_b64 v184, v[112:113] offset:1024
	s_or_b64 exec, exec, s[2:3]
	v_add_f32_e32 v112, v76, v77
	v_add_f32_e32 v113, v78, v79
	v_add_f32_e32 v112, v112, v113
	v_mul_f32_e32 v113, v77, v77
	v_mul_f32_e32 v114, v79, v79
	v_fmac_f32_e32 v113, v76, v76
	v_fmac_f32_e32 v114, v78, v78
	v_add_f32_e32 v113, v113, v114
	v_add_f32_e32 v114, v80, v81
	v_add_f32_e32 v115, v82, v83
	v_add_f32_e32 v112, 0, v112
	v_add_f32_e32 v114, v114, v115
	v_add_f32_e32 v112, v114, v112
	v_mul_f32_e32 v114, v81, v81
	v_mul_f32_e32 v115, v83, v83
	v_fmac_f32_e32 v114, v80, v80
	v_fmac_f32_e32 v115, v82, v82
	v_add_f32_e32 v114, v114, v115
	v_add_f32_e32 v113, v113, v114
	v_add_f32_e32 v114, v68, v69
	v_add_f32_e32 v115, v70, v71
	v_add_f32_e32 v114, v114, v115
	v_add_f32_e32 v112, v114, v112
	v_mul_f32_e32 v114, v69, v69
	v_mul_f32_e32 v115, v71, v71
	v_fmac_f32_e32 v114, v68, v68
	v_fmac_f32_e32 v115, v70, v70
	v_add_f32_e32 v114, v114, v115
	v_add_f32_e32 v113, v114, v113
	v_add_f32_e32 v114, v72, v73
	v_add_f32_e32 v115, v74, v75
	v_add_f32_e32 v114, v114, v115
	v_add_f32_e32 v112, v114, v112
	v_mul_f32_e32 v114, v73, v73
	v_mul_f32_e32 v115, v75, v75
	v_fmac_f32_e32 v114, v72, v72
	v_fmac_f32_e32 v115, v74, v74
	v_add_f32_e32 v114, v114, v115
	v_add_f32_e32 v113, v114, v113
	v_mov_b32_e32 v114, v112
	v_mov_b32_e32 v115, v113
	s_nop 0
	v_permlane16_swap_b32_e32 v112, v114
	v_permlane16_swap_b32_e32 v113, v115
	v_add_f32_e32 v112, v112, v114
	v_add_f32_e32 v113, v113, v115
	v_mov_b32_e32 v114, v112
	v_mov_b32_e32 v115, v113
	s_nop 0
	v_permlane32_swap_b32_e32 v112, v114
	v_permlane32_swap_b32_e32 v113, v115
	s_and_saveexec_b64 s[2:3], s[8:9]
	v_pk_add_f32 v[112:113], v[112:113], v[114:115]
	ds_write_b64 v184, v[112:113] offset:1536
	s_or_b64 exec, exec, s[2:3]
	v_add_f32_e32 v112, v60, v61
	v_add_f32_e32 v113, v62, v63
	v_add_f32_e32 v112, v112, v113
	v_mul_f32_e32 v113, v61, v61
	v_mul_f32_e32 v114, v63, v63
	v_fmac_f32_e32 v113, v60, v60
	v_fmac_f32_e32 v114, v62, v62
	v_add_f32_e32 v113, v113, v114
	v_add_f32_e32 v114, v64, v65
	v_add_f32_e32 v115, v66, v67
	v_add_f32_e32 v112, 0, v112
	v_add_f32_e32 v114, v114, v115
	v_add_f32_e32 v112, v114, v112
	v_mul_f32_e32 v114, v65, v65
	v_mul_f32_e32 v115, v67, v67
	v_fmac_f32_e32 v114, v64, v64
	v_fmac_f32_e32 v115, v66, v66
	v_add_f32_e32 v114, v114, v115
	v_add_f32_e32 v113, v113, v114
	v_add_f32_e32 v114, v52, v53
	v_add_f32_e32 v115, v54, v55
	v_add_f32_e32 v114, v114, v115
	v_add_f32_e32 v112, v114, v112
	v_mul_f32_e32 v114, v53, v53
	v_mul_f32_e32 v115, v55, v55
	v_fmac_f32_e32 v114, v52, v52
	v_fmac_f32_e32 v115, v54, v54
	v_add_f32_e32 v114, v114, v115
	v_add_f32_e32 v113, v114, v113
	v_add_f32_e32 v114, v56, v57
	v_add_f32_e32 v115, v58, v59
	v_add_f32_e32 v114, v114, v115
	v_add_f32_e32 v112, v114, v112
	v_mul_f32_e32 v114, v57, v57
	v_mul_f32_e32 v115, v59, v59
	v_fmac_f32_e32 v114, v56, v56
	v_fmac_f32_e32 v115, v58, v58
	v_add_f32_e32 v114, v114, v115
	v_add_f32_e32 v113, v114, v113
	v_mov_b32_e32 v114, v112
	v_mov_b32_e32 v115, v113
	s_nop 0
	v_permlane16_swap_b32_e32 v112, v114
	v_permlane16_swap_b32_e32 v113, v115
	v_add_f32_e32 v112, v112, v114
	v_add_f32_e32 v113, v113, v115
	v_mov_b32_e32 v114, v112
	v_mov_b32_e32 v115, v113
	s_nop 0
	v_permlane32_swap_b32_e32 v112, v114
	v_permlane32_swap_b32_e32 v113, v115
	s_and_saveexec_b64 s[2:3], s[8:9]
	v_pk_add_f32 v[112:113], v[112:113], v[114:115]
	ds_write_b64 v184, v[112:113] offset:4096
	s_or_b64 exec, exec, s[2:3]
	v_add_f32_e32 v112, v44, v45
	v_add_f32_e32 v113, v46, v47
	v_add_f32_e32 v112, v112, v113
	v_mul_f32_e32 v113, v45, v45
	v_mul_f32_e32 v114, v47, v47
	v_fmac_f32_e32 v113, v44, v44
	v_fmac_f32_e32 v114, v46, v46
	v_add_f32_e32 v113, v113, v114
	v_add_f32_e32 v114, v48, v49
	v_add_f32_e32 v115, v50, v51
	v_add_f32_e32 v112, 0, v112
	v_add_f32_e32 v114, v114, v115
	v_add_f32_e32 v112, v114, v112
	v_mul_f32_e32 v114, v49, v49
	v_mul_f32_e32 v115, v51, v51
	v_fmac_f32_e32 v114, v48, v48
	v_fmac_f32_e32 v115, v50, v50
	v_add_f32_e32 v114, v114, v115
	v_add_f32_e32 v113, v113, v114
	v_add_f32_e32 v114, v36, v37
	v_add_f32_e32 v115, v38, v39
	v_add_f32_e32 v114, v114, v115
	v_add_f32_e32 v112, v114, v112
	v_mul_f32_e32 v114, v37, v37
	v_mul_f32_e32 v115, v39, v39
	v_fmac_f32_e32 v114, v36, v36
	v_fmac_f32_e32 v115, v38, v38
	v_add_f32_e32 v114, v114, v115
	v_add_f32_e32 v113, v114, v113
	v_add_f32_e32 v114, v40, v41
	v_add_f32_e32 v115, v42, v43
	v_add_f32_e32 v114, v114, v115
	v_add_f32_e32 v112, v114, v112
	v_mul_f32_e32 v114, v41, v41
	v_mul_f32_e32 v115, v43, v43
	v_fmac_f32_e32 v114, v40, v40
	v_fmac_f32_e32 v115, v42, v42
	v_add_f32_e32 v114, v114, v115
	v_add_f32_e32 v113, v114, v113
	v_mov_b32_e32 v114, v112
	v_mov_b32_e32 v115, v113
	s_nop 0
	v_permlane16_swap_b32_e32 v112, v114
	v_permlane16_swap_b32_e32 v113, v115
	v_add_f32_e32 v112, v112, v114
	v_add_f32_e32 v113, v113, v115
	v_mov_b32_e32 v114, v112
	v_mov_b32_e32 v115, v113
	s_nop 0
	v_permlane32_swap_b32_e32 v112, v114
	v_permlane32_swap_b32_e32 v113, v115
	s_and_saveexec_b64 s[2:3], s[8:9]
	v_pk_add_f32 v[112:113], v[112:113], v[114:115]
	ds_write_b64 v184, v[112:113] offset:4608
	s_or_b64 exec, exec, s[2:3]
	v_add_f32_e32 v112, v28, v29
	v_add_f32_e32 v113, v30, v31
	v_add_f32_e32 v112, v112, v113
	v_mul_f32_e32 v113, v29, v29
	v_mul_f32_e32 v114, v31, v31
	v_fmac_f32_e32 v113, v28, v28
	v_fmac_f32_e32 v114, v30, v30
	v_add_f32_e32 v113, v113, v114
	v_add_f32_e32 v114, v32, v33
	v_add_f32_e32 v115, v34, v35
	v_add_f32_e32 v112, 0, v112
	v_add_f32_e32 v114, v114, v115
	v_add_f32_e32 v112, v114, v112
	v_mul_f32_e32 v114, v33, v33
	v_mul_f32_e32 v115, v35, v35
	v_fmac_f32_e32 v114, v32, v32
	v_fmac_f32_e32 v115, v34, v34
	v_add_f32_e32 v114, v114, v115
	v_add_f32_e32 v113, v113, v114
	v_add_f32_e32 v114, v20, v21
	v_add_f32_e32 v115, v22, v23
	v_add_f32_e32 v114, v114, v115
	v_add_f32_e32 v112, v114, v112
	v_mul_f32_e32 v114, v21, v21
	v_mul_f32_e32 v115, v23, v23
	v_fmac_f32_e32 v114, v20, v20
	v_fmac_f32_e32 v115, v22, v22
	v_add_f32_e32 v114, v114, v115
	v_add_f32_e32 v113, v114, v113
	v_add_f32_e32 v114, v24, v25
	v_add_f32_e32 v115, v26, v27
	v_add_f32_e32 v114, v114, v115
	v_add_f32_e32 v112, v114, v112
	v_mul_f32_e32 v114, v25, v25
	v_mul_f32_e32 v115, v27, v27
	v_fmac_f32_e32 v114, v24, v24
	v_fmac_f32_e32 v115, v26, v26
	v_add_f32_e32 v114, v114, v115
	v_add_f32_e32 v113, v114, v113
	v_mov_b32_e32 v114, v112
	v_mov_b32_e32 v115, v113
	s_nop 0
	v_permlane16_swap_b32_e32 v112, v114
	v_permlane16_swap_b32_e32 v113, v115
	v_add_f32_e32 v112, v112, v114
	v_add_f32_e32 v113, v113, v115
	v_mov_b32_e32 v114, v112
	v_mov_b32_e32 v115, v113
	s_nop 0
	v_permlane32_swap_b32_e32 v112, v114
	v_permlane32_swap_b32_e32 v113, v115
	s_and_saveexec_b64 s[2:3], s[8:9]
	v_pk_add_f32 v[112:113], v[112:113], v[114:115]
	ds_write_b64 v184, v[112:113] offset:5120
	s_or_b64 exec, exec, s[2:3]
	v_add_f32_e32 v112, v12, v13
	v_add_f32_e32 v113, v14, v15
	v_add_f32_e32 v112, v112, v113
	v_mul_f32_e32 v113, v13, v13
	v_mul_f32_e32 v114, v15, v15
	v_fmac_f32_e32 v113, v12, v12
	v_fmac_f32_e32 v114, v14, v14
	v_add_f32_e32 v113, v113, v114
	v_add_f32_e32 v114, v16, v17
	v_add_f32_e32 v115, v18, v19
	v_add_f32_e32 v112, 0, v112
	v_add_f32_e32 v114, v114, v115
	v_add_f32_e32 v112, v114, v112
	v_mul_f32_e32 v114, v17, v17
	v_mul_f32_e32 v115, v19, v19
	v_fmac_f32_e32 v114, v16, v16
	v_fmac_f32_e32 v115, v18, v18
	v_add_f32_e32 v114, v114, v115
	v_add_f32_e32 v113, v113, v114
	v_add_f32_e32 v114, v4, v5
	v_add_f32_e32 v115, v6, v7
	v_add_f32_e32 v114, v114, v115
	v_add_f32_e32 v112, v114, v112
	v_mul_f32_e32 v114, v5, v5
	v_mul_f32_e32 v115, v7, v7
	v_fmac_f32_e32 v114, v4, v4
	v_fmac_f32_e32 v115, v6, v6
	v_add_f32_e32 v114, v114, v115
	v_add_f32_e32 v113, v114, v113
	v_add_f32_e32 v114, v8, v9
	v_add_f32_e32 v115, v10, v11
	v_add_f32_e32 v114, v114, v115
	v_add_f32_e32 v112, v114, v112
	v_mul_f32_e32 v114, v9, v9
	v_mul_f32_e32 v115, v11, v11
	v_fmac_f32_e32 v114, v8, v8
	v_fmac_f32_e32 v115, v10, v10
	v_add_f32_e32 v114, v114, v115
	v_add_f32_e32 v113, v114, v113
	v_mov_b32_e32 v114, v112
	v_mov_b32_e32 v115, v113
	s_nop 0
	v_permlane16_swap_b32_e32 v112, v114
	v_permlane16_swap_b32_e32 v113, v115
	v_add_f32_e32 v112, v112, v114
	v_add_f32_e32 v113, v113, v115
	v_mov_b32_e32 v114, v112
	v_mov_b32_e32 v115, v113
	s_nop 0
	v_permlane32_swap_b32_e32 v112, v114
	v_permlane32_swap_b32_e32 v113, v115
	s_and_saveexec_b64 s[2:3], s[8:9]
	v_pk_add_f32 v[112:113], v[112:113], v[114:115]
	ds_write_b64 v184, v[112:113] offset:5632
	s_or_b64 exec, exec, s[2:3]
	s_waitcnt lgkmcnt(0)
	s_barrier
	s_add_u32 s14, s22, 0xac00000
	v_add_u32_e32 v170, s66, v180
	s_addc_u32 s15, s23, 0
	v_ashrrev_i32_e32 v171, 31, v170
	s_and_saveexec_b64 s[2:3], s[10:11]
	s_cbranch_execz .LBB0_257
	ds_read_b128 v[112:115], v183
	ds_read_b128 v[120:123], v183 offset:16
	s_ashr_i32 s83, s82, 31
	s_waitcnt lgkmcnt(1)
	v_mov_b32_e32 v124, v112
	s_waitcnt lgkmcnt(0)
	v_mov_b32_e32 v125, v120
	v_mov_b32_e32 v126, v114
	v_mov_b32_e32 v127, v122
	v_pk_add_f32 v[124:125], v[124:125], v[126:127]
	v_mov_b32_e32 v120, v113
	v_mov_b32_e32 v122, v115
	v_add_f32_e32 v114, v124, v125
	v_pk_add_f32 v[112:113], v[120:121], v[122:123]
	s_nop 0
	v_add_f32_e32 v113, v112, v113
	v_mul_f32_e32 v112, 0x3b800000, v114
	v_fma_f32 v113, -v114, v112, v113
	v_lshlrev_b64 v[114:115], 6, v[170:171]
	v_lshl_add_u64 v[114:115], s[14:15], 0, v[114:115]
	v_max_f32_e32 v113, 0, v113
	v_lshl_add_u64 v[114:115], s[82:83], 3, v[114:115]
	global_store_dwordx2 v[114:115], v[112:113], off sc1

.LBB0_647:
	v_readlane_b32 s5, v254, 35
	s_waitcnt lgkmcnt(0)
	s_add_u32 s5, s22, s5
	s_addc_u32 s19, s23, 0
	s_add_u32 s5, s5, 0x100000
	s_addc_u32 s49, s19, 0
	s_lshr_b32 s19, s72, 14
	s_add_i32 s19, s19, 8
	s_ashr_i32 s29, s18, 4
	s_and_b64 s[54:55], s[54:55], exec
	s_cselect_b32 s19, s19, s29
	s_lshl_b32 s29, s28, 8
	s_mul_hi_i32 s55, s19, 0x4800
	s_mul_i32 s54, s19, 0x4800
	s_or_b32 s63, s29, s51
	s_lshl_b64 s[54:55], s[54:55], 2
	v_or_b32_e32 v132, s63, v179
	s_add_u32 s66, s5, s54
	s_addc_u32 s67, s49, s55
	v_ashrrev_i32_e32 v133, 31, v132
	v_lshl_add_u64 v[132:133], v[132:133], 2, s[66:67]
	s_mov_b32 s19, 0xa000
	s_mov_b64 s[66:67], 0xa000
	v_add_co_u32_e32 v142, vcc, s19, v132
	v_lshl_add_u64 v[140:141], v[132:133], 0, s[66:67]
	s_nop 0
	v_addc_co_u32_e32 v143, vcc, 0, v133, vcc
	global_load_dwordx4 v[132:135], v[140:141], off offset:64
	global_load_dwordx4 v[136:139], v[140:141], off offset:512
	s_nop 0
	global_load_dwordx4 v[142:145], v[142:143], off
	s_nop 0
	global_load_dwordx4 v[154:157], v[140:141], off offset:576
	v_or3_b32 v140, v183, s51, v181
	v_add_u32_e32 v140, s29, v140
	v_ashrrev_i32_e32 v141, 31, v140
	v_lshl_add_u64 v[152:153], v[140:141], 2, s[60:61]
	v_readlane_b32 s60, v254, 54
	v_lshl_add_u64 v[140:141], v[152:153], 0, s[6:7]
	v_readlane_b32 s61, v254, 55
	global_load_dwordx4 v[146:149], v[140:141], off nt
	global_load_dwordx4 v[158:161], v[140:141], off offset:512 nt
	v_lshl_add_u64 v[140:141], v[152:153], 0, s[60:61]
	v_readlane_b32 s60, v254, 58
	global_load_dwordx4 v[174:177], v[140:141], off nt
	global_load_dwordx4 v[190:193], v[140:141], off offset:512 nt
	v_lshl_add_u64 v[140:141], v[152:153], 0, s[34:35]
	v_readlane_b32 s61, v254, 59
	global_load_dwordx4 v[194:197], v[140:141], off nt
	global_load_dwordx4 v[198:201], v[140:141], off offset:512 nt
	v_lshl_add_u64 v[140:141], v[152:153], 0, s[60:61]
	v_readlane_b32 s60, v254, 62
	global_load_dwordx4 v[202:205], v[140:141], off nt
	global_load_dwordx4 v[214:217], v[140:141], off offset:512 nt
	v_lshl_add_u64 v[140:141], v[152:153], 0, s[40:41]
	v_readlane_b32 s61, v254, 63
	global_load_dwordx4 v[218:221], v[140:141], off nt
	global_load_dwordx4 v[222:225], v[140:141], off offset:512 nt
	v_lshl_add_u64 v[140:141], v[152:153], 0, s[60:61]
	v_readlane_b32 s60, v255, 2
	global_load_dwordx4 v[226:229], v[140:141], off nt
	global_load_dwordx4 v[230:233], v[140:141], off offset:512 nt
	v_lshl_add_u64 v[140:141], v[152:153], 0, s[46:47]
	v_readlane_b32 s61, v255, 3
	global_load_dwordx4 v[234:237], v[140:141], off nt
	global_load_dwordx4 v[238:241], v[140:141], off offset:512 nt
	v_lshl_add_u64 v[140:141], v[152:153], 0, s[60:61]
	global_load_dwordx4 v[250:253], v[140:141], off nt
	global_load_dwordx4 v[206:209], v[140:141], off offset:512 nt
	v_lshl_add_u64 v[140:141], v[152:153], 0, s[52:53]
	global_load_dword v189, v[140:141], off
	global_load_dword v189, v[140:141], off offset:512
	v_readlane_b32 s60, v255, 6
	v_readlane_b32 s61, v255, 7
	s_nop 1
	v_lshl_add_u64 v[140:141], v[152:153], 0, s[60:61]
	global_load_dword v189, v[140:141], off
	global_load_dword v189, v[140:141], off offset:512
	v_lshl_add_u64 v[140:141], v[152:153], 0, s[58:59]
	global_load_dword v189, v[140:141], off
	global_load_dword v189, v[140:141], off offset:512
	v_readlane_b32 s60, v255, 12
	v_readlane_b32 s61, v255, 13
	s_nop 1
	v_lshl_add_u64 v[140:141], v[152:153], 0, s[60:61]
	global_load_dword v189, v[140:141], off
	global_load_dword v189, v[140:141], off offset:512
	v_lshl_add_u64 v[140:141], v[152:153], 0, s[64:65]
	global_load_dword v189, v[140:141], off
	global_load_dword v189, v[140:141], off offset:512
	v_readlane_b32 s60, v254, 40
	v_readlane_b32 s61, v254, 41
	s_nop 1
	v_lshl_add_u64 v[140:141], v[152:153], 0, s[60:61]
	global_load_dword v189, v[140:141], off
	global_load_dword v189, v[140:141], off offset:512
	v_lshl_add_u64 v[140:141], v[152:153], 0, s[78:79]
	global_load_dword v189, v[140:141], off
	global_load_dword v189, v[140:141], off offset:512
	v_readlane_b32 s60, v254, 42
	v_readlane_b32 s61, v254, 43
	s_nop 1
	v_lshl_add_u64 v[140:141], v[152:153], 0, s[60:61]
	global_load_dword v189, v[140:141], off
	global_load_dword v189, v[140:141], off offset:512
	s_waitcnt vmcnt(16)
	ds_write_b128 v182, v[146:149]
	ds_write_b128 v182, v[174:177] offset:1152
	ds_read_b128 v[146:149], v180
	ds_read_b128 v[174:177], v180 offset:64
	ds_write_b128 v182, v[158:161]
	ds_write_b128 v182, v[190:193] offset:1152
	ds_read_b128 v[158:161], v180
	ds_read_b128 v[190:193], v180 offset:64
	s_waitcnt lgkmcnt(5)
	v_pk_mul_f32 v[146:147], v[146:147], s[80:81] op_sel_hi:[1,0]
	v_pk_add_f32 v[142:143], v[142:143], 1.0 op_sel_hi:[1,0]
	ds_write_b128 v182, v[194:197]
	ds_write_b128 v182, v[202:205] offset:1152
	v_pk_add_f32 v[140:141], v[144:145], 1.0 op_sel_hi:[1,0]
	v_pk_fma_f32 v[128:129], v[128:129], v[142:143], v[146:147]
	s_waitcnt lgkmcnt(6)
	v_pk_mul_f32 v[144:145], v[176:177], s[80:81] op_sel_hi:[1,0]
	v_pk_mul_f32 v[146:147], v[174:175], s[80:81] op_sel_hi:[1,0]
	ds_read_b128 v[174:177], v180
	ds_read_b128 v[194:197], v180 offset:64
	v_pk_mul_f32 v[148:149], v[148:149], s[80:81] op_sel_hi:[1,0]
	v_pk_add_f32 v[150:151], v[132:133], 1.0 op_sel_hi:[1,0]
	v_pk_fma_f32 v[130:131], v[130:131], v[140:141], v[148:149]
	v_pk_add_f32 v[148:149], v[134:135], 1.0 op_sel_hi:[1,0]
	v_pk_fma_f32 v[132:133], v[124:125], v[150:151], v[146:147]
	v_pk_fma_f32 v[134:135], v[126:127], v[148:149], v[144:145]
	s_waitcnt lgkmcnt(5)
	v_pk_mul_f32 v[144:145], v[160:161], s[80:81] op_sel_hi:[1,0]
	v_pk_add_f32 v[124:125], v[138:139], 1.0 op_sel_hi:[1,0]
	ds_write_b128 v182, v[198:201]
	ds_write_b128 v182, v[214:217] offset:1152
	v_pk_mul_f32 v[146:147], v[158:159], s[80:81] op_sel_hi:[1,0]
	v_pk_fma_f32 v[138:139], v[122:123], v[124:125], v[144:145]
	s_waitcnt lgkmcnt(6)
	v_pk_mul_f32 v[144:145], v[192:193], s[80:81] op_sel_hi:[1,0]
	v_pk_mul_f32 v[162:163], v[190:191], s[80:81] op_sel_hi:[1,0]
	ds_read_b128 v[158:161], v180
	ds_read_b128 v[190:193], v180 offset:64
	v_pk_add_f32 v[126:127], v[136:137], 1.0 op_sel_hi:[1,0]
	v_pk_add_f32 v[122:123], v[154:155], 1.0 op_sel_hi:[1,0]
	v_pk_fma_f32 v[136:137], v[120:121], v[126:127], v[146:147]
	v_pk_add_f32 v[120:121], v[156:157], 1.0 op_sel_hi:[1,0]
	s_nop 0
	v_pk_fma_f32 v[146:147], v[106:107], v[120:121], v[144:145]
	v_pk_fma_f32 v[144:145], v[104:105], v[122:123], v[162:163]
	s_waitcnt lgkmcnt(5)
	v_pk_mul_f32 v[104:105], v[176:177], s[80:81] op_sel_hi:[1,0]
	v_pk_mul_f32 v[106:107], v[174:175], s[80:81] op_sel_hi:[1,0]
	v_pk_fma_f32 v[110:111], v[110:111], v[140:141], v[104:105]
	v_pk_fma_f32 v[108:109], v[108:109], v[142:143], v[106:107]
	s_waitcnt lgkmcnt(4)
	v_pk_mul_f32 v[104:105], v[196:197], s[80:81] op_sel_hi:[1,0]
	v_pk_mul_f32 v[106:107], v[194:195], s[80:81] op_sel_hi:[1,0]
	v_pk_fma_f32 v[118:119], v[118:119], v[148:149], v[104:105]
	v_pk_fma_f32 v[116:117], v[116:117], v[150:151], v[106:107]
	s_waitcnt lgkmcnt(1)
	v_pk_mul_f32 v[104:105], v[160:161], s[80:81] op_sel_hi:[1,0]
	v_pk_mul_f32 v[106:107], v[158:159], s[80:81] op_sel_hi:[1,0]
	v_pk_fma_f32 v[102:103], v[102:103], v[124:125], v[104:105]
	s_waitcnt lgkmcnt(0)
	v_pk_mul_f32 v[104:105], v[192:193], s[80:81] op_sel_hi:[1,0]
	v_pk_mul_f32 v[154:155], v[190:191], s[80:81] op_sel_hi:[1,0]
	v_pk_fma_f32 v[100:101], v[100:101], v[126:127], v[106:107]
	v_pk_fma_f32 v[106:107], v[98:99], v[120:121], v[104:105]
	v_pk_fma_f32 v[104:105], v[96:97], v[122:123], v[154:155]
	v_readlane_b32 s60, v255, 6
	v_lshl_add_u64 v[96:97], v[152:153], 0, s[52:53]
	v_readlane_b32 s61, v255, 7
	global_load_dwordx4 v[154:157], v[96:97], off nt
	global_load_dwordx4 v[158:161], v[96:97], off offset:512 nt
	v_lshl_add_u64 v[96:97], v[152:153], 0, s[60:61]
	v_readlane_b32 s60, v255, 12
	global_load_dwordx4 v[174:177], v[96:97], off nt
	global_load_dwordx4 v[190:193], v[96:97], off offset:512 nt
	v_lshl_add_u64 v[96:97], v[152:153], 0, s[58:59]
	v_readlane_b32 s61, v255, 13
	global_load_dwordx4 v[194:197], v[96:97], off nt
	global_load_dwordx4 v[198:201], v[96:97], off offset:512 nt
	v_lshl_add_u64 v[96:97], v[152:153], 0, s[60:61]
	global_load_dwordx4 v[202:205], v[96:97], off nt
	global_load_dwordx4 v[214:217], v[96:97], off offset:512 nt
	ds_write_b128 v182, v[218:221]
	ds_write_b128 v182, v[226:229] offset:1152
	ds_read_b128 v[96:99], v180
	ds_read_b128 v[218:221], v180 offset:64
	ds_write_b128 v182, v[222:225]
	ds_write_b128 v182, v[230:233] offset:1152
	ds_read_b128 v[222:225], v180
	ds_read_b128 v[226:229], v180 offset:64
	ds_write_b128 v182, v[234:237]
	ds_write_b128 v182, v[250:253] offset:1152
	ds_read_b128 v[230:233], v180
	ds_read_b128 v[234:237], v180 offset:64
	s_waitcnt lgkmcnt(9)
	v_pk_mul_f32 v[96:97], v[96:97], s[80:81] op_sel_hi:[1,0]
	v_pk_mul_f32 v[98:99], v[98:99], s[80:81] op_sel_hi:[1,0]
	v_pk_fma_f32 v[92:93], v[92:93], v[142:143], v[96:97]
	s_waitcnt lgkmcnt(8)
	v_pk_mul_f32 v[96:97], v[220:221], s[80:81] op_sel_hi:[1,0]
	v_pk_mul_f32 v[162:163], v[218:219], s[80:81] op_sel_hi:[1,0]
	v_pk_fma_f32 v[94:95], v[94:95], v[140:141], v[98:99]
	v_pk_fma_f32 v[98:99], v[90:91], v[148:149], v[96:97]
	v_pk_fma_f32 v[96:97], v[88:89], v[150:151], v[162:163]
	ds_write_b128 v182, v[238:241]
	ds_write_b128 v182, v[206:209] offset:1152
	ds_read_b128 v[206:209], v180
	ds_read_b128 v[218:221], v180 offset:64
	s_waitcnt lgkmcnt(9)
	v_pk_mul_f32 v[88:89], v[224:225], s[80:81] op_sel_hi:[1,0]
	v_pk_mul_f32 v[90:91], v[222:223], s[80:81] op_sel_hi:[1,0]
	v_pk_fma_f32 v[86:87], v[86:87], v[124:125], v[88:89]
	s_waitcnt lgkmcnt(8)
	v_pk_mul_f32 v[88:89], v[228:229], s[80:81] op_sel_hi:[1,0]
	v_pk_mul_f32 v[162:163], v[226:227], s[80:81] op_sel_hi:[1,0]
	v_pk_fma_f32 v[84:85], v[84:85], v[126:127], v[90:91]
	v_pk_fma_f32 v[90:91], v[74:75], v[120:121], v[88:89]
	v_pk_fma_f32 v[88:89], v[72:73], v[122:123], v[162:163]
	s_waitcnt lgkmcnt(5)
	v_pk_mul_f32 v[72:73], v[232:233], s[80:81] op_sel_hi:[1,0]
	v_pk_mul_f32 v[74:75], v[230:231], s[80:81] op_sel_hi:[1,0]
	v_pk_fma_f32 v[78:79], v[78:79], v[140:141], v[72:73]
	v_pk_fma_f32 v[76:77], v[76:77], v[142:143], v[74:75]
	s_waitcnt lgkmcnt(4)
	v_pk_mul_f32 v[72:73], v[236:237], s[80:81] op_sel_hi:[1,0]
	v_pk_mul_f32 v[74:75], v[234:235], s[80:81] op_sel_hi:[1,0]
	v_pk_fma_f32 v[82:83], v[82:83], v[148:149], v[72:73]
	v_pk_fma_f32 v[80:81], v[80:81], v[150:151], v[74:75]
	s_waitcnt lgkmcnt(1)
	v_pk_mul_f32 v[72:73], v[208:209], s[80:81] op_sel_hi:[1,0]
	v_pk_mul_f32 v[74:75], v[206:207], s[80:81] op_sel_hi:[1,0]
	v_pk_fma_f32 v[70:71], v[70:71], v[124:125], v[72:73]
	s_waitcnt lgkmcnt(0)
	v_pk_mul_f32 v[72:73], v[220:221], s[80:81] op_sel_hi:[1,0]
	v_pk_mul_f32 v[162:163], v[218:219], s[80:81] op_sel_hi:[1,0]
	v_pk_fma_f32 v[68:69], v[68:69], v[126:127], v[74:75]
	v_pk_fma_f32 v[74:75], v[66:67], v[120:121], v[72:73]
	v_pk_fma_f32 v[72:73], v[64:65], v[122:123], v[162:163]
	v_readlane_b32 s60, v254, 40
	v_lshl_add_u64 v[64:65], v[152:153], 0, s[64:65]
	v_readlane_b32 s61, v254, 41
	global_load_dwordx4 v[206:209], v[64:65], off nt
	global_load_dwordx4 v[218:221], v[64:65], off offset:512 nt
	v_lshl_add_u64 v[64:65], v[152:153], 0, s[60:61]
	v_readlane_b32 s60, v254, 42
	global_load_dwordx4 v[222:225], v[64:65], off nt
	global_load_dwordx4 v[226:229], v[64:65], off offset:512 nt
	v_lshl_add_u64 v[64:65], v[152:153], 0, s[78:79]
	v_readlane_b32 s61, v254, 43
	global_load_dwordx4 v[230:233], v[64:65], off nt
	global_load_dwordx4 v[234:237], v[64:65], off offset:512 nt
	v_lshl_add_u64 v[64:65], v[152:153], 0, s[60:61]
	global_load_dwordx4 v[238:241], v[64:65], off nt
	global_load_dwordx4 v[250:253], v[64:65], off offset:512 nt
	s_waitcnt vmcnt(15)
	ds_write_b128 v182, v[154:157]
	s_waitcnt vmcnt(13)
	ds_write_b128 v182, v[174:177] offset:1152
	ds_read_b128 v[64:67], v180
	ds_read_b128 v[152:155], v180 offset:64
	ds_write_b128 v182, v[158:161]
	s_waitcnt vmcnt(12)
	ds_write_b128 v182, v[190:193] offset:1152
	ds_read_b128 v[156:159], v180
	ds_read_b128 v[160:163], v180 offset:64
	s_waitcnt vmcnt(11)
	ds_write_b128 v182, v[194:197]
	s_waitcnt vmcnt(9)
	ds_write_b128 v182, v[202:205] offset:1152
	ds_read_b128 v[174:177], v180
	ds_read_b128 v[190:193], v180 offset:64
	s_waitcnt lgkmcnt(9)
	v_pk_mul_f32 v[64:65], v[64:65], s[80:81] op_sel_hi:[1,0]
	v_pk_mul_f32 v[66:67], v[66:67], s[80:81] op_sel_hi:[1,0]
	v_pk_fma_f32 v[60:61], v[60:61], v[142:143], v[64:65]
	s_waitcnt lgkmcnt(8)
	v_pk_mul_f32 v[64:65], v[154:155], s[80:81] op_sel_hi:[1,0]
	v_pk_mul_f32 v[152:153], v[152:153], s[80:81] op_sel_hi:[1,0]
	v_pk_fma_f32 v[62:63], v[62:63], v[140:141], v[66:67]
	v_pk_fma_f32 v[66:67], v[58:59], v[148:149], v[64:65]
	v_pk_fma_f32 v[64:65], v[56:57], v[150:151], v[152:153]
	ds_write_b128 v182, v[198:201]
	s_waitcnt vmcnt(8)
	ds_write_b128 v182, v[214:217] offset:1152
	s_waitcnt lgkmcnt(7)
	v_pk_mul_f32 v[56:57], v[158:159], s[80:81] op_sel_hi:[1,0]
	v_pk_mul_f32 v[58:59], v[156:157], s[80:81] op_sel_hi:[1,0]
	ds_read_b128 v[152:155], v180
	ds_read_b128 v[156:159], v180 offset:64
	v_pk_fma_f32 v[54:55], v[54:55], v[124:125], v[56:57]
	s_waitcnt lgkmcnt(8)
	v_pk_mul_f32 v[56:57], v[162:163], s[80:81] op_sel_hi:[1,0]
	v_pk_mul_f32 v[160:161], v[160:161], s[80:81] op_sel_hi:[1,0]
	v_pk_fma_f32 v[52:53], v[52:53], v[126:127], v[58:59]
	v_pk_fma_f32 v[58:59], v[42:43], v[120:121], v[56:57]
	v_pk_fma_f32 v[56:57], v[40:41], v[122:123], v[160:161]
	s_waitcnt lgkmcnt(5)
	v_pk_mul_f32 v[40:41], v[176:177], s[80:81] op_sel_hi:[1,0]
	v_pk_mul_f32 v[42:43], v[174:175], s[80:81] op_sel_hi:[1,0]
	v_pk_fma_f32 v[46:47], v[46:47], v[140:141], v[40:41]
	v_pk_fma_f32 v[44:45], v[44:45], v[142:143], v[42:43]
	s_waitcnt lgkmcnt(4)
	v_pk_mul_f32 v[40:41], v[192:193], s[80:81] op_sel_hi:[1,0]
	v_pk_mul_f32 v[42:43], v[190:191], s[80:81] op_sel_hi:[1,0]
	v_pk_fma_f32 v[50:51], v[50:51], v[148:149], v[40:41]
	v_pk_fma_f32 v[48:49], v[48:49], v[150:151], v[42:43]
	s_waitcnt lgkmcnt(1)
	v_pk_mul_f32 v[40:41], v[154:155], s[80:81] op_sel_hi:[1,0]
	v_pk_mul_f32 v[42:43], v[152:153], s[80:81] op_sel_hi:[1,0]
	v_pk_fma_f32 v[38:39], v[38:39], v[124:125], v[40:41]
	s_waitcnt lgkmcnt(0)
	v_pk_mul_f32 v[40:41], v[158:159], s[80:81] op_sel_hi:[1,0]
	v_pk_mul_f32 v[152:153], v[156:157], s[80:81] op_sel_hi:[1,0]
	v_pk_fma_f32 v[36:37], v[36:37], v[126:127], v[42:43]
	v_pk_fma_f32 v[42:43], v[34:35], v[120:121], v[40:41]
	v_pk_fma_f32 v[40:41], v[32:33], v[122:123], v[152:153]
	s_nop 0
	s_waitcnt vmcnt(7)
	ds_write_b128 v182, v[206:209]
	s_waitcnt vmcnt(5)
	ds_write_b128 v182, v[222:225] offset:1152
	ds_read_b128 v[32:35], v180
	ds_read_b128 v[152:155], v180 offset:64
	ds_write_b128 v182, v[218:221]
	s_waitcnt vmcnt(4)
	ds_write_b128 v182, v[226:229] offset:1152
	ds_read_b128 v[156:159], v180
	ds_read_b128 v[160:163], v180 offset:64
	s_waitcnt vmcnt(3)
	ds_write_b128 v182, v[230:233]
	s_waitcnt vmcnt(1)
	ds_write_b128 v182, v[238:241] offset:1152
	ds_read_b128 v[174:177], v180
	ds_read_b128 v[190:193], v180 offset:64
	s_waitcnt lgkmcnt(9)
	v_pk_mul_f32 v[32:33], v[32:33], s[80:81] op_sel_hi:[1,0]
	v_pk_mul_f32 v[34:35], v[34:35], s[80:81] op_sel_hi:[1,0]
	v_pk_fma_f32 v[28:29], v[28:29], v[142:143], v[32:33]
	s_waitcnt lgkmcnt(8)
	v_pk_mul_f32 v[32:33], v[154:155], s[80:81] op_sel_hi:[1,0]
	v_pk_mul_f32 v[152:153], v[152:153], s[80:81] op_sel_hi:[1,0]
	v_pk_fma_f32 v[30:31], v[30:31], v[140:141], v[34:35]
	v_pk_fma_f32 v[34:35], v[26:27], v[148:149], v[32:33]
	v_pk_fma_f32 v[32:33], v[24:25], v[150:151], v[152:153]
	ds_write_b128 v182, v[234:237]
	s_waitcnt vmcnt(0)
	ds_write_b128 v182, v[250:253] offset:1152
	s_waitcnt lgkmcnt(7)
	v_pk_mul_f32 v[24:25], v[158:159], s[80:81] op_sel_hi:[1,0]
	v_pk_mul_f32 v[26:27], v[156:157], s[80:81] op_sel_hi:[1,0]
	ds_read_b128 v[152:155], v180
	ds_read_b128 v[156:159], v180 offset:64
	v_pk_fma_f32 v[22:23], v[22:23], v[124:125], v[24:25]
	s_waitcnt lgkmcnt(8)
	v_pk_mul_f32 v[24:25], v[162:163], s[80:81] op_sel_hi:[1,0]
	v_pk_mul_f32 v[160:161], v[160:161], s[80:81] op_sel_hi:[1,0]
	v_pk_fma_f32 v[20:21], v[20:21], v[126:127], v[26:27]
	v_pk_fma_f32 v[26:27], v[14:15], v[120:121], v[24:25]
	v_pk_fma_f32 v[24:25], v[12:13], v[122:123], v[160:161]
	s_waitcnt lgkmcnt(5)
	v_pk_mul_f32 v[12:13], v[176:177], s[80:81] op_sel_hi:[1,0]
	v_pk_mul_f32 v[160:161], v[174:175], s[80:81] op_sel_hi:[1,0]
	v_pk_fma_f32 v[14:15], v[114:115], v[140:141], v[12:13]
	v_pk_fma_f32 v[12:13], v[112:113], v[142:143], v[160:161]
	s_waitcnt lgkmcnt(4)
	v_pk_mul_f32 v[112:113], v[192:193], s[80:81] op_sel_hi:[1,0]
	v_pk_mul_f32 v[114:115], v[190:191], s[80:81] op_sel_hi:[1,0]
	v_pk_fma_f32 v[18:19], v[18:19], v[148:149], v[112:113]
	v_pk_fma_f32 v[16:17], v[16:17], v[150:151], v[114:115]
	s_waitcnt lgkmcnt(1)
	v_pk_mul_f32 v[112:113], v[154:155], s[80:81] op_sel_hi:[1,0]
	v_pk_mul_f32 v[114:115], v[152:153], s[80:81] op_sel_hi:[1,0]
	v_pk_fma_f32 v[6:7], v[6:7], v[124:125], v[112:113]
	s_waitcnt lgkmcnt(0)
	v_pk_mul_f32 v[112:113], v[158:159], s[80:81] op_sel_hi:[1,0]
	v_pk_fma_f32 v[4:5], v[4:5], v[126:127], v[114:115]
	v_pk_mul_f32 v[114:115], v[156:157], s[80:81] op_sel_hi:[1,0]
	v_pk_fma_f32 v[10:11], v[10:11], v[120:121], v[112:113]
	v_add_f32_e32 v112, v128, v129
	v_add_f32_e32 v113, v130, v131
	v_pk_fma_f32 v[8:9], v[8:9], v[122:123], v[114:115]
	v_add_f32_e32 v112, v112, v113
	v_mul_f32_e32 v113, v129, v129
	v_mul_f32_e32 v114, v131, v131
	v_fmac_f32_e32 v113, v128, v128
	v_fmac_f32_e32 v114, v130, v130
	v_add_f32_e32 v113, v113, v114
	v_add_f32_e32 v114, v132, v133
	v_add_f32_e32 v115, v134, v135
	v_add_f32_e32 v112, 0, v112
	v_add_f32_e32 v114, v114, v115
	v_add_f32_e32 v112, v114, v112
	v_mul_f32_e32 v114, v133, v133
	v_mul_f32_e32 v115, v135, v135
	v_fmac_f32_e32 v114, v132, v132
	v_fmac_f32_e32 v115, v134, v134
	v_add_f32_e32 v114, v114, v115
	v_add_f32_e32 v113, v113, v114
	v_add_f32_e32 v114, v136, v137
	v_add_f32_e32 v115, v138, v139
	v_add_f32_e32 v114, v114, v115
	v_add_f32_e32 v112, v114, v112
	v_mul_f32_e32 v114, v137, v137
	v_mul_f32_e32 v115, v139, v139
	v_fmac_f32_e32 v114, v136, v136
	v_fmac_f32_e32 v115, v138, v138
	v_add_f32_e32 v114, v114, v115
	v_add_f32_e32 v113, v114, v113
	v_add_f32_e32 v114, v144, v145
	v_add_f32_e32 v115, v146, v147
	v_add_f32_e32 v114, v114, v115
	v_add_f32_e32 v112, v114, v112
	v_mul_f32_e32 v114, v145, v145
	v_mul_f32_e32 v115, v147, v147
	v_fmac_f32_e32 v114, v144, v144
	v_fmac_f32_e32 v115, v146, v146
	v_add_f32_e32 v114, v114, v115
	v_add_f32_e32 v113, v114, v113
	v_mov_b32_e32 v114, v112
	v_mov_b32_e32 v115, v113
	s_nop 0
	v_permlane16_swap_b32_e32 v112, v114
	v_permlane16_swap_b32_e32 v113, v115
	v_add_f32_e32 v112, v112, v114
	v_add_f32_e32 v113, v113, v115
	v_mov_b32_e32 v114, v112
	v_mov_b32_e32 v115, v113
	s_nop 0
	v_permlane32_swap_b32_e32 v112, v114
	v_permlane32_swap_b32_e32 v113, v115
	s_and_saveexec_b64 s[60:61], s[8:9]
	v_pk_add_f32 v[112:113], v[112:113], v[114:115]
	ds_write_b64 v188, v[112:113]
	s_or_b64 exec, exec, s[60:61]
	v_add_f32_e32 v112, v108, v109
	v_add_f32_e32 v113, v110, v111
	v_add_f32_e32 v112, v112, v113
	v_mul_f32_e32 v113, v109, v109
	v_mul_f32_e32 v114, v111, v111
	v_fmac_f32_e32 v113, v108, v108
	v_fmac_f32_e32 v114, v110, v110
	v_add_f32_e32 v113, v113, v114
	v_add_f32_e32 v114, v116, v117
	v_add_f32_e32 v115, v118, v119
	v_add_f32_e32 v112, 0, v112
	v_add_f32_e32 v114, v114, v115
	v_add_f32_e32 v112, v114, v112
	v_mul_f32_e32 v114, v117, v117
	v_mul_f32_e32 v115, v119, v119
	v_fmac_f32_e32 v114, v116, v116
	v_fmac_f32_e32 v115, v118, v118
	v_add_f32_e32 v114, v114, v115
	v_add_f32_e32 v113, v113, v114
	v_add_f32_e32 v114, v100, v101
	v_add_f32_e32 v115, v102, v103
	v_add_f32_e32 v114, v114, v115
	v_add_f32_e32 v112, v114, v112
	v_mul_f32_e32 v114, v101, v101
	v_mul_f32_e32 v115, v103, v103
	v_fmac_f32_e32 v114, v100, v100
	v_fmac_f32_e32 v115, v102, v102
	v_add_f32_e32 v114, v114, v115
	v_add_f32_e32 v113, v114, v113
	v_add_f32_e32 v114, v104, v105
	v_add_f32_e32 v115, v106, v107
	v_add_f32_e32 v114, v114, v115
	v_add_f32_e32 v112, v114, v112
	v_mul_f32_e32 v114, v105, v105
	v_mul_f32_e32 v115, v107, v107
	v_fmac_f32_e32 v114, v104, v104
	v_fmac_f32_e32 v115, v106, v106
	v_add_f32_e32 v114, v114, v115
	v_add_f32_e32 v113, v114, v113
	v_mov_b32_e32 v114, v112
	v_mov_b32_e32 v115, v113
	s_nop 0
	v_permlane16_swap_b32_e32 v112, v114
	v_permlane16_swap_b32_e32 v113, v115
	v_add_f32_e32 v112, v112, v114
	v_add_f32_e32 v113, v113, v115
	v_mov_b32_e32 v114, v112
	v_mov_b32_e32 v115, v113
	s_nop 0
	v_permlane32_swap_b32_e32 v112, v114
	v_permlane32_swap_b32_e32 v113, v115
	s_and_saveexec_b64 s[60:61], s[8:9]
	v_pk_add_f32 v[112:113], v[112:113], v[114:115]
	ds_write_b64 v188, v[112:113] offset:512
	s_or_b64 exec, exec, s[60:61]
	v_add_f32_e32 v112, v92, v93
	v_add_f32_e32 v113, v94, v95
	v_add_f32_e32 v112, v112, v113
	v_mul_f32_e32 v113, v93, v93
	v_mul_f32_e32 v114, v95, v95
	v_fmac_f32_e32 v113, v92, v92
	v_fmac_f32_e32 v114, v94, v94
	v_add_f32_e32 v113, v113, v114
	v_add_f32_e32 v114, v96, v97
	v_add_f32_e32 v115, v98, v99
	v_add_f32_e32 v112, 0, v112
	v_add_f32_e32 v114, v114, v115
	v_add_f32_e32 v112, v114, v112
	v_mul_f32_e32 v114, v97, v97
	v_mul_f32_e32 v115, v99, v99
	v_fmac_f32_e32 v114, v96, v96
	v_fmac_f32_e32 v115, v98, v98
	v_add_f32_e32 v114, v114, v115
	v_add_f32_e32 v113, v113, v114
	v_add_f32_e32 v114, v84, v85
	v_add_f32_e32 v115, v86, v87
	v_add_f32_e32 v114, v114, v115
	v_add_f32_e32 v112, v114, v112
	v_mul_f32_e32 v114, v85, v85
	v_mul_f32_e32 v115, v87, v87
	v_fmac_f32_e32 v114, v84, v84
	v_fmac_f32_e32 v115, v86, v86
	v_add_f32_e32 v114, v114, v115
	v_add_f32_e32 v113, v114, v113
	v_add_f32_e32 v114, v88, v89
	v_add_f32_e32 v115, v90, v91
	v_add_f32_e32 v114, v114, v115
	v_add_f32_e32 v112, v114, v112
	v_mul_f32_e32 v114, v89, v89
	v_mul_f32_e32 v115, v91, v91
	v_fmac_f32_e32 v114, v88, v88
	v_fmac_f32_e32 v115, v90, v90
	v_add_f32_e32 v114, v114, v115
	v_add_f32_e32 v113, v114, v113
	v_mov_b32_e32 v114, v112
	v_mov_b32_e32 v115, v113
	s_nop 0
	v_permlane16_swap_b32_e32 v112, v114
	v_permlane16_swap_b32_e32 v113, v115
	v_add_f32_e32 v112, v112, v114
	v_add_f32_e32 v113, v113, v115
	v_mov_b32_e32 v114, v112
	v_mov_b32_e32 v115, v113
	s_nop 0
	v_permlane32_swap_b32_e32 v112, v114
	v_permlane32_swap_b32_e32 v113, v115
	s_and_saveexec_b64 s[60:61], s[8:9]
	v_pk_add_f32 v[112:113], v[112:113], v[114:115]
	ds_write_b64 v188, v[112:113] offset:1024
	s_or_b64 exec, exec, s[60:61]
	v_add_f32_e32 v112, v76, v77
	v_add_f32_e32 v113, v78, v79
	v_add_f32_e32 v112, v112, v113
	v_mul_f32_e32 v113, v77, v77
	v_mul_f32_e32 v114, v79, v79
	v_fmac_f32_e32 v113, v76, v76
	v_fmac_f32_e32 v114, v78, v78
	v_add_f32_e32 v113, v113, v114
	v_add_f32_e32 v114, v80, v81
	v_add_f32_e32 v115, v82, v83
	v_add_f32_e32 v112, 0, v112
	v_add_f32_e32 v114, v114, v115
	v_add_f32_e32 v112, v114, v112
	v_mul_f32_e32 v114, v81, v81
	v_mul_f32_e32 v115, v83, v83
	v_fmac_f32_e32 v114, v80, v80
	v_fmac_f32_e32 v115, v82, v82
	v_add_f32_e32 v114, v114, v115
	v_add_f32_e32 v113, v113, v114
	v_add_f32_e32 v114, v68, v69
	v_add_f32_e32 v115, v70, v71
	v_add_f32_e32 v114, v114, v115
	v_add_f32_e32 v112, v114, v112
	v_mul_f32_e32 v114, v69, v69
	v_mul_f32_e32 v115, v71, v71
	v_fmac_f32_e32 v114, v68, v68
	v_fmac_f32_e32 v115, v70, v70
	v_add_f32_e32 v114, v114, v115
	v_add_f32_e32 v113, v114, v113
	v_add_f32_e32 v114, v72, v73
	v_add_f32_e32 v115, v74, v75
	v_add_f32_e32 v114, v114, v115
	v_add_f32_e32 v112, v114, v112
	v_mul_f32_e32 v114, v73, v73
	v_mul_f32_e32 v115, v75, v75
	v_fmac_f32_e32 v114, v72, v72
	v_fmac_f32_e32 v115, v74, v74
	v_add_f32_e32 v114, v114, v115
	v_add_f32_e32 v113, v114, v113
	v_mov_b32_e32 v114, v112
	v_mov_b32_e32 v115, v113
	s_nop 0
	v_permlane16_swap_b32_e32 v112, v114
	v_permlane16_swap_b32_e32 v113, v115
	v_add_f32_e32 v112, v112, v114
	v_add_f32_e32 v113, v113, v115
	v_mov_b32_e32 v114, v112
	v_mov_b32_e32 v115, v113
	s_nop 0
	v_permlane32_swap_b32_e32 v112, v114
	v_permlane32_swap_b32_e32 v113, v115
	s_and_saveexec_b64 s[60:61], s[8:9]
	v_pk_add_f32 v[112:113], v[112:113], v[114:115]
	ds_write_b64 v188, v[112:113] offset:1536
	s_or_b64 exec, exec, s[60:61]
	v_add_f32_e32 v112, v60, v61
	v_add_f32_e32 v113, v62, v63
	v_add_f32_e32 v112, v112, v113
	v_mul_f32_e32 v113, v61, v61
	v_mul_f32_e32 v114, v63, v63
	v_fmac_f32_e32 v113, v60, v60
	v_fmac_f32_e32 v114, v62, v62
	v_add_f32_e32 v113, v113, v114
	v_add_f32_e32 v114, v64, v65
	v_add_f32_e32 v115, v66, v67
	v_add_f32_e32 v112, 0, v112
	v_add_f32_e32 v114, v114, v115
	v_add_f32_e32 v112, v114, v112
	v_mul_f32_e32 v114, v65, v65
	v_mul_f32_e32 v115, v67, v67
	v_fmac_f32_e32 v114, v64, v64
	v_fmac_f32_e32 v115, v66, v66
	v_add_f32_e32 v114, v114, v115
	v_add_f32_e32 v113, v113, v114
	v_add_f32_e32 v114, v52, v53
	v_add_f32_e32 v115, v54, v55
	v_add_f32_e32 v114, v114, v115
	v_add_f32_e32 v112, v114, v112
	v_mul_f32_e32 v114, v53, v53
	v_mul_f32_e32 v115, v55, v55
	v_fmac_f32_e32 v114, v52, v52
	v_fmac_f32_e32 v115, v54, v54
	v_add_f32_e32 v114, v114, v115
	v_add_f32_e32 v113, v114, v113
	v_add_f32_e32 v114, v56, v57
	v_add_f32_e32 v115, v58, v59
	v_add_f32_e32 v114, v114, v115
	v_add_f32_e32 v112, v114, v112
	v_mul_f32_e32 v114, v57, v57
	v_mul_f32_e32 v115, v59, v59
	v_fmac_f32_e32 v114, v56, v56
	v_fmac_f32_e32 v115, v58, v58
	v_add_f32_e32 v114, v114, v115
	v_add_f32_e32 v113, v114, v113
	v_mov_b32_e32 v114, v112
	v_mov_b32_e32 v115, v113
	s_nop 0
	v_permlane16_swap_b32_e32 v112, v114
	v_permlane16_swap_b32_e32 v113, v115
	v_add_f32_e32 v112, v112, v114
	v_add_f32_e32 v113, v113, v115
	v_mov_b32_e32 v114, v112
	v_mov_b32_e32 v115, v113
	s_nop 0
	v_permlane32_swap_b32_e32 v112, v114
	v_permlane32_swap_b32_e32 v113, v115
	s_and_saveexec_b64 s[60:61], s[8:9]
	v_pk_add_f32 v[112:113], v[112:113], v[114:115]
	ds_write_b64 v188, v[112:113] offset:4096
	s_or_b64 exec, exec, s[60:61]
	v_add_f32_e32 v112, v44, v45
	v_add_f32_e32 v113, v46, v47
	v_add_f32_e32 v112, v112, v113
	v_mul_f32_e32 v113, v45, v45
	v_mul_f32_e32 v114, v47, v47
	v_fmac_f32_e32 v113, v44, v44
	v_fmac_f32_e32 v114, v46, v46
	v_add_f32_e32 v113, v113, v114
	v_add_f32_e32 v114, v48, v49
	v_add_f32_e32 v115, v50, v51
	v_add_f32_e32 v112, 0, v112
	v_add_f32_e32 v114, v114, v115
	v_add_f32_e32 v112, v114, v112
	v_mul_f32_e32 v114, v49, v49
	v_mul_f32_e32 v115, v51, v51
	v_fmac_f32_e32 v114, v48, v48
	v_fmac_f32_e32 v115, v50, v50
	v_add_f32_e32 v114, v114, v115
	v_add_f32_e32 v113, v113, v114
	v_add_f32_e32 v114, v36, v37
	v_add_f32_e32 v115, v38, v39
	v_add_f32_e32 v114, v114, v115
	v_add_f32_e32 v112, v114, v112
	v_mul_f32_e32 v114, v37, v37
	v_mul_f32_e32 v115, v39, v39
	v_fmac_f32_e32 v114, v36, v36
	v_fmac_f32_e32 v115, v38, v38
	v_add_f32_e32 v114, v114, v115
	v_add_f32_e32 v113, v114, v113
	v_add_f32_e32 v114, v40, v41
	v_add_f32_e32 v115, v42, v43
	v_add_f32_e32 v114, v114, v115
	v_add_f32_e32 v112, v114, v112
	v_mul_f32_e32 v114, v41, v41
	v_mul_f32_e32 v115, v43, v43
	v_fmac_f32_e32 v114, v40, v40
	v_fmac_f32_e32 v115, v42, v42
	v_add_f32_e32 v114, v114, v115
	v_add_f32_e32 v113, v114, v113
	v_mov_b32_e32 v114, v112
	v_mov_b32_e32 v115, v113
	s_nop 0
	v_permlane16_swap_b32_e32 v112, v114
	v_permlane16_swap_b32_e32 v113, v115
	v_add_f32_e32 v112, v112, v114
	v_add_f32_e32 v113, v113, v115
	v_mov_b32_e32 v114, v112
	v_mov_b32_e32 v115, v113
	s_nop 0
	v_permlane32_swap_b32_e32 v112, v114
	v_permlane32_swap_b32_e32 v113, v115
	s_and_saveexec_b64 s[60:61], s[8:9]
	v_pk_add_f32 v[112:113], v[112:113], v[114:115]
	ds_write_b64 v188, v[112:113] offset:4608
	s_or_b64 exec, exec, s[60:61]
	v_add_f32_e32 v112, v28, v29
	v_add_f32_e32 v113, v30, v31
	v_add_f32_e32 v112, v112, v113
	v_mul_f32_e32 v113, v29, v29
	v_mul_f32_e32 v114, v31, v31
	v_fmac_f32_e32 v113, v28, v28
	v_fmac_f32_e32 v114, v30, v30
	v_add_f32_e32 v113, v113, v114
	v_add_f32_e32 v114, v32, v33
	v_add_f32_e32 v115, v34, v35
	v_add_f32_e32 v112, 0, v112
	v_add_f32_e32 v114, v114, v115
	v_add_f32_e32 v112, v114, v112
	v_mul_f32_e32 v114, v33, v33
	v_mul_f32_e32 v115, v35, v35
	v_fmac_f32_e32 v114, v32, v32
	v_fmac_f32_e32 v115, v34, v34
	v_add_f32_e32 v114, v114, v115
	v_add_f32_e32 v113, v113, v114
	v_add_f32_e32 v114, v20, v21
	v_add_f32_e32 v115, v22, v23
	v_add_f32_e32 v114, v114, v115
	v_add_f32_e32 v112, v114, v112
	v_mul_f32_e32 v114, v21, v21
	v_mul_f32_e32 v115, v23, v23
	v_fmac_f32_e32 v114, v20, v20
	v_fmac_f32_e32 v115, v22, v22
	v_add_f32_e32 v114, v114, v115
	v_add_f32_e32 v113, v114, v113
	v_add_f32_e32 v114, v24, v25
	v_add_f32_e32 v115, v26, v27
	v_add_f32_e32 v114, v114, v115
	v_add_f32_e32 v112, v114, v112
	v_mul_f32_e32 v114, v25, v25
	v_mul_f32_e32 v115, v27, v27
	v_fmac_f32_e32 v114, v24, v24
	v_fmac_f32_e32 v115, v26, v26
	v_add_f32_e32 v114, v114, v115
	v_add_f32_e32 v113, v114, v113
	v_mov_b32_e32 v114, v112
	v_mov_b32_e32 v115, v113
	s_nop 0
	v_permlane16_swap_b32_e32 v112, v114
	v_permlane16_swap_b32_e32 v113, v115
	v_add_f32_e32 v112, v112, v114
	v_add_f32_e32 v113, v113, v115
	v_mov_b32_e32 v114, v112
	v_mov_b32_e32 v115, v113
	s_nop 0
	v_permlane32_swap_b32_e32 v112, v114
	v_permlane32_swap_b32_e32 v113, v115
	s_and_saveexec_b64 s[60:61], s[8:9]
	v_pk_add_f32 v[112:113], v[112:113], v[114:115]
	ds_write_b64 v188, v[112:113] offset:5120
	s_or_b64 exec, exec, s[60:61]
	v_add_f32_e32 v112, v12, v13
	v_add_f32_e32 v113, v14, v15
	v_add_f32_e32 v112, v112, v113
	v_mul_f32_e32 v113, v13, v13
	v_mul_f32_e32 v114, v15, v15
	v_fmac_f32_e32 v113, v12, v12
	v_fmac_f32_e32 v114, v14, v14
	v_add_f32_e32 v113, v113, v114
	v_add_f32_e32 v114, v16, v17
	v_add_f32_e32 v115, v18, v19
	v_add_f32_e32 v112, 0, v112
	v_add_f32_e32 v114, v114, v115
	v_add_f32_e32 v112, v114, v112
	v_mul_f32_e32 v114, v17, v17
	v_mul_f32_e32 v115, v19, v19
	v_fmac_f32_e32 v114, v16, v16
	v_fmac_f32_e32 v115, v18, v18
	v_add_f32_e32 v114, v114, v115
	v_add_f32_e32 v113, v113, v114
	v_add_f32_e32 v114, v4, v5
	v_add_f32_e32 v115, v6, v7
	v_add_f32_e32 v114, v114, v115
	v_add_f32_e32 v112, v114, v112
	v_mul_f32_e32 v114, v5, v5
	v_mul_f32_e32 v115, v7, v7
	v_fmac_f32_e32 v114, v4, v4
	v_fmac_f32_e32 v115, v6, v6
	v_add_f32_e32 v114, v114, v115
	v_add_f32_e32 v113, v114, v113
	v_add_f32_e32 v114, v8, v9
	v_add_f32_e32 v115, v10, v11
	v_add_f32_e32 v114, v114, v115
	v_add_f32_e32 v112, v114, v112
	v_mul_f32_e32 v114, v9, v9
	v_mul_f32_e32 v115, v11, v11
	v_fmac_f32_e32 v114, v8, v8
	v_fmac_f32_e32 v115, v10, v10
	v_add_f32_e32 v114, v114, v115
	v_add_f32_e32 v113, v114, v113
	v_mov_b32_e32 v114, v112
	v_mov_b32_e32 v115, v113
	s_nop 0
	v_permlane16_swap_b32_e32 v112, v114
	v_permlane16_swap_b32_e32 v113, v115
	v_add_f32_e32 v112, v112, v114
	v_add_f32_e32 v113, v113, v115
	v_mov_b32_e32 v114, v112
	v_mov_b32_e32 v115, v113
	s_nop 0
	v_permlane32_swap_b32_e32 v112, v114
	v_permlane32_swap_b32_e32 v113, v115
	s_and_saveexec_b64 s[60:61], s[8:9]
	v_pk_add_f32 v[112:113], v[112:113], v[114:115]
	ds_write_b64 v188, v[112:113] offset:5632
	s_or_b64 exec, exec, s[60:61]
	s_waitcnt lgkmcnt(0)
	s_barrier
	s_add_u32 s60, s22, 0x2ac00000
	v_add_u32_e32 v174, s82, v184
	s_addc_u32 s61, s23, 0
	v_ashrrev_i32_e32 v175, 31, v174
	s_and_saveexec_b64 vcc, s[10:11]
	s_cbranch_execz .LBB0_665
	ds_read_b128 v[112:115], v187
	ds_read_b128 v[120:123], v187 offset:16
	s_ashr_i32 s29, s28, 31
	s_waitcnt lgkmcnt(1)
	v_mov_b32_e32 v124, v112
	s_waitcnt lgkmcnt(0)
	v_mov_b32_e32 v125, v120
	v_mov_b32_e32 v126, v114
	v_mov_b32_e32 v127, v122
	v_pk_add_f32 v[124:125], v[124:125], v[126:127]
	v_mov_b32_e32 v120, v113
	v_mov_b32_e32 v122, v115
	v_add_f32_e32 v114, v124, v125
	v_pk_add_f32 v[112:113], v[120:121], v[122:123]
	s_nop 0
	v_add_f32_e32 v113, v112, v113
	v_mul_f32_e32 v112, 0x3b800000, v114
	v_fma_f32 v113, -v114, v112, v113
	v_lshlrev_b64 v[114:115], 6, v[174:175]
	v_lshl_add_u64 v[114:115], s[60:61], 0, v[114:115]
	v_max_f32_e32 v113, 0, v113
	v_lshl_add_u64 v[114:115], s[28:29], 3, v[114:115]
	global_store_dwordx2 v[114:115], v[112:113], off sc1

.LBB0_817:
	v_readlane_b32 s6, v254, 35
	s_waitcnt lgkmcnt(0)
	s_add_u32 s6, s26, s6
	s_addc_u32 s7, s27, 0
	s_add_u32 s45, s6, 0x100000
	s_addc_u32 s59, s7, 0
	s_lshr_b32 s6, s72, 14
	s_add_i32 s60, s6, 8
	s_ashr_i32 s61, s64, 4
	s_and_b64 s[6:7], s[18:19], exec
	s_cselect_b32 s6, s60, s61
	s_lshl_b32 s60, s82, 8
	s_mul_hi_i32 s7, s6, 0x4800
	s_mulk_i32 s6, 0x4800
	s_or_b32 s69, s60, s47
	s_lshl_b64 s[18:19], s[6:7], 2
	v_or_b32_e32 v132, s69, v181
	s_add_u32 s6, s45, s18
	s_addc_u32 s7, s59, s19
	v_ashrrev_i32_e32 v133, 31, v132
	v_lshl_add_u64 v[132:133], v[132:133], 2, s[6:7]
	s_mov_b32 s6, 0x10000
	v_add_co_u32_e32 v140, vcc, s6, v132
	v_lshl_add_u64 v[144:145], v[132:133], 0, s[76:77]
	s_nop 0
	v_addc_co_u32_e32 v141, vcc, 0, v133, vcc
	global_load_dwordx4 v[132:135], v[144:145], off offset:64
	global_load_dwordx4 v[136:139], v[144:145], off offset:512
	s_nop 0
	global_load_dwordx4 v[140:143], v[140:141], off
	s_nop 0
	global_load_dwordx4 v[152:155], v[144:145], off offset:576
	v_or3_b32 v144, v185, s47, v183
	v_add_u32_e32 v144, s60, v144
	v_ashrrev_i32_e32 v145, 31, v144
	v_readlane_b32 s6, v254, 46
	v_lshl_add_u64 v[178:179], v[144:145], 2, s[56:57]
	v_readlane_b32 s7, v254, 47
	v_lshl_add_u64 v[148:149], v[178:179], 0, s[36:37]
	global_load_dwordx4 v[144:147], v[148:149], off nt
	s_nop 0
	global_load_dwordx4 v[148:151], v[148:149], off offset:512 nt
	v_lshl_add_u64 v[166:167], v[178:179], 0, s[6:7]
	v_readlane_b32 s6, v254, 50
	global_load_dwordx4 v[156:159], v[166:167], off nt
	s_nop 0
	global_load_dwordx4 v[166:169], v[166:167], off offset:512 nt
	v_readlane_b32 s7, v254, 51
	v_lshl_add_u64 v[174:175], v[178:179], 0, s[42:43]
	global_load_dwordx4 v[170:173], v[174:175], off nt
	s_nop 0
	global_load_dwordx4 v[174:177], v[174:175], off offset:512 nt
	v_lshl_add_u64 v[196:197], v[178:179], 0, s[6:7]
	v_readlane_b32 s6, v254, 54
	v_readlane_b32 s7, v254, 55
	global_load_dwordx4 v[192:195], v[196:197], off nt
	s_nop 0
	global_load_dwordx4 v[196:199], v[196:197], off offset:512 nt
	v_lshl_add_u64 v[204:205], v[178:179], 0, s[48:49]
	v_lshl_add_u64 v[208:209], v[178:179], 0, s[6:7]
	v_readlane_b32 s6, v254, 58
	global_load_dwordx4 v[200:203], v[204:205], off nt
	s_nop 0
	global_load_dwordx4 v[204:207], v[204:205], off offset:512 nt
	s_nop 0
	global_load_dwordx4 v[214:217], v[208:209], off nt
	global_load_dwordx4 v[218:221], v[208:209], off offset:512 nt
	v_lshl_add_u64 v[208:209], v[178:179], 0, s[54:55]
	v_readlane_b32 s7, v254, 59
	global_load_dwordx4 v[222:225], v[208:209], off nt
	global_load_dwordx4 v[226:229], v[208:209], off offset:512 nt
	v_lshl_add_u64 v[208:209], v[178:179], 0, s[6:7]
	global_load_dwordx4 v[230:233], v[208:209], off nt
	global_load_dwordx4 v[234:237], v[208:209], off offset:512 nt
	v_lshl_add_u64 v[208:209], v[178:179], 0, s[62:63]
	global_load_dword v210, v[208:209], off
	global_load_dword v210, v[208:209], off offset:512
	v_readlane_b32 s6, v254, 60
	v_readlane_b32 s7, v254, 61
	s_nop 1
	v_lshl_add_u64 v[208:209], v[178:179], 0, s[6:7]
	global_load_dword v210, v[208:209], off
	global_load_dword v210, v[208:209], off offset:512
	v_lshl_add_u64 v[208:209], v[178:179], 0, s[96:97]
	global_load_dword v210, v[208:209], off
	global_load_dword v210, v[208:209], off offset:512
	v_readlane_b32 s6, v254, 62
	v_readlane_b32 s7, v254, 63
	s_nop 1
	v_lshl_add_u64 v[208:209], v[178:179], 0, s[6:7]
	global_load_dword v210, v[208:209], off
	global_load_dword v210, v[208:209], off offset:512
	v_lshl_add_u64 v[208:209], v[178:179], 0, s[70:71]
	global_load_dword v210, v[208:209], off
	global_load_dword v210, v[208:209], off offset:512
	v_readlane_b32 s6, v255, 0
	v_readlane_b32 s7, v255, 1
	s_nop 1
	v_lshl_add_u64 v[208:209], v[178:179], 0, s[6:7]
	global_load_dword v210, v[208:209], off
	global_load_dword v210, v[208:209], off offset:512
	v_lshl_add_u64 v[208:209], v[178:179], 0, s[14:15]
	global_load_dword v210, v[208:209], off
	global_load_dword v210, v[208:209], off offset:512
	v_readlane_b32 s6, v255, 2
	v_readlane_b32 s7, v255, 3
	s_nop 1
	v_lshl_add_u64 v[208:209], v[178:179], 0, s[6:7]
	global_load_dword v210, v[208:209], off
	global_load_dword v210, v[208:209], off offset:512
	s_waitcnt vmcnt(16)
	ds_write_b128 v184, v[144:147]
	ds_write_b128 v184, v[156:159] offset:1152
	ds_read_b128 v[144:147], v182
	ds_read_b128 v[238:241], v182 offset:64
	ds_write_b128 v184, v[148:151]
	ds_write_b128 v184, v[166:169] offset:1152
	ds_read_b128 v[148:151], v182
	ds_read_b128 v[250:253], v182 offset:64
	v_pk_add_f32 v[142:143], v[142:143], 1.0 op_sel_hi:[1,0]
	v_pk_add_f32 v[140:141], v[140:141], 1.0 op_sel_hi:[1,0]
	s_waitcnt lgkmcnt(5)
	v_pk_mul_f32 v[146:147], v[146:147], s[80:81] op_sel_hi:[1,0]
	v_pk_mul_f32 v[144:145], v[144:145], s[80:81] op_sel_hi:[1,0]
	v_pk_mul_f32 v[156:157], v[142:143], 0.5 op_sel_hi:[1,0]
	v_pk_mul_f32 v[158:159], v[140:141], 0.5 op_sel_hi:[1,0]
	ds_write_b128 v184, v[170:173]
	ds_write_b128 v184, v[192:195] offset:1152
	v_pk_fma_f32 v[142:143], v[130:131], v[156:157], v[146:147]
	v_pk_fma_f32 v[140:141], v[128:129], v[158:159], v[144:145]
	ds_read_b128 v[128:131], v182
	ds_read_b128 v[192:195], v182 offset:64
	v_pk_add_f32 v[134:135], v[134:135], 1.0 op_sel_hi:[1,0]
	v_pk_add_f32 v[132:133], v[132:133], 1.0 op_sel_hi:[1,0]
	s_waitcnt lgkmcnt(8)
	v_pk_mul_f32 v[144:145], v[240:241], s[80:81] op_sel_hi:[1,0]
	v_pk_mul_f32 v[208:209], v[238:239], s[80:81] op_sel_hi:[1,0]
	v_pk_mul_f32 v[166:167], v[134:135], 0.5 op_sel_hi:[1,0]
	v_pk_mul_f32 v[168:169], v[132:133], 0.5 op_sel_hi:[1,0]
	v_pk_fma_f32 v[146:147], v[126:127], v[166:167], v[144:145]
	v_pk_fma_f32 v[144:145], v[124:125], v[168:169], v[208:209]
	v_pk_add_f32 v[132:133], v[138:139], 1.0 op_sel_hi:[1,0]
	v_pk_add_f32 v[134:135], v[136:137], 1.0 op_sel_hi:[1,0]
	s_waitcnt lgkmcnt(5)
	v_pk_mul_f32 v[124:125], v[150:151], s[80:81] op_sel_hi:[1,0]
	v_pk_mul_f32 v[126:127], v[148:149], s[80:81] op_sel_hi:[1,0]
	v_pk_mul_f32 v[170:171], v[132:133], 0.5 op_sel_hi:[1,0]
	v_pk_mul_f32 v[172:173], v[134:135], 0.5 op_sel_hi:[1,0]
	ds_write_b128 v184, v[174:177]
	ds_write_b128 v184, v[196:199] offset:1152
	v_pk_fma_f32 v[150:151], v[122:123], v[170:171], v[124:125]
	v_pk_fma_f32 v[148:149], v[120:121], v[172:173], v[126:127]
	ds_read_b128 v[120:123], v182
	ds_read_b128 v[196:199], v182 offset:64
	v_pk_add_f32 v[132:133], v[154:155], 1.0 op_sel_hi:[1,0]
	v_pk_add_f32 v[134:135], v[152:153], 1.0 op_sel_hi:[1,0]
	s_waitcnt lgkmcnt(8)
	v_pk_mul_f32 v[124:125], v[252:253], s[80:81] op_sel_hi:[1,0]
	v_pk_mul_f32 v[126:127], v[250:251], s[80:81] op_sel_hi:[1,0]
	v_pk_mul_f32 v[174:175], v[132:133], 0.5 op_sel_hi:[1,0]
	v_pk_mul_f32 v[176:177], v[134:135], 0.5 op_sel_hi:[1,0]
	v_pk_fma_f32 v[154:155], v[110:111], v[174:175], v[124:125]
	v_pk_fma_f32 v[152:153], v[108:109], v[176:177], v[126:127]
	s_waitcnt lgkmcnt(5)
	v_pk_mul_f32 v[108:109], v[130:131], s[80:81] op_sel_hi:[1,0]
	v_pk_mul_f32 v[110:111], v[128:129], s[80:81] op_sel_hi:[1,0]
	v_pk_fma_f32 v[134:135], v[118:119], v[156:157], v[108:109]
	v_pk_fma_f32 v[132:133], v[116:117], v[158:159], v[110:111]
	s_waitcnt lgkmcnt(4)
	v_pk_mul_f32 v[108:109], v[194:195], s[80:81] op_sel_hi:[1,0]
	v_pk_mul_f32 v[110:111], v[192:193], s[80:81] op_sel_hi:[1,0]
	v_pk_fma_f32 v[138:139], v[114:115], v[166:167], v[108:109]
	v_pk_fma_f32 v[136:137], v[112:113], v[168:169], v[110:111]
	s_waitcnt lgkmcnt(1)
	v_pk_mul_f32 v[108:109], v[122:123], s[80:81] op_sel_hi:[1,0]
	v_pk_mul_f32 v[110:111], v[120:121], s[80:81] op_sel_hi:[1,0]
	v_pk_fma_f32 v[126:127], v[106:107], v[170:171], v[108:109]
	v_pk_fma_f32 v[124:125], v[104:105], v[172:173], v[110:111]
	s_waitcnt lgkmcnt(0)
	v_pk_mul_f32 v[104:105], v[198:199], s[80:81] op_sel_hi:[1,0]
	v_pk_mul_f32 v[106:107], v[196:197], s[80:81] op_sel_hi:[1,0]
	v_readlane_b32 s6, v254, 60
	v_pk_fma_f32 v[130:131], v[102:103], v[174:175], v[104:105]
	v_pk_fma_f32 v[128:129], v[100:101], v[176:177], v[106:107]
	v_readlane_b32 s7, v254, 61
	v_lshl_add_u64 v[104:105], v[178:179], 0, s[62:63]
	global_load_dwordx4 v[100:103], v[104:105], off nt
	s_nop 0
	global_load_dwordx4 v[104:107], v[104:105], off offset:512 nt
	v_lshl_add_u64 v[108:109], v[178:179], 0, s[6:7]
	v_readlane_b32 s6, v254, 62
	global_load_dwordx4 v[112:115], v[108:109], off nt
	global_load_dwordx4 v[192:195], v[108:109], off offset:512 nt
	v_lshl_add_u64 v[108:109], v[178:179], 0, s[96:97]
	v_readlane_b32 s7, v254, 63
	global_load_dwordx4 v[196:199], v[108:109], off nt
	global_load_dwordx4 v[238:241], v[108:109], off offset:512 nt
	v_lshl_add_u64 v[108:109], v[178:179], 0, s[6:7]
	global_load_dwordx4 v[250:253], v[108:109], off nt
	global_load_dwordx4 v[208:211], v[108:109], off offset:512 nt
	ds_write_b128 v184, v[200:203]
	ds_write_b128 v184, v[214:217] offset:1152
	ds_read_b128 v[108:111], v182
	ds_read_b128 v[120:123], v182 offset:64
	ds_write_b128 v184, v[204:207]
	ds_write_b128 v184, v[218:221] offset:1152
	ds_read_b128 v[200:203], v182
	ds_read_b128 v[204:207], v182 offset:64
	ds_write_b128 v184, v[222:225]
	ds_write_b128 v184, v[230:233] offset:1152
	ds_read_b128 v[214:217], v182
	ds_read_b128 v[218:221], v182 offset:64
	s_waitcnt lgkmcnt(9)
	v_pk_mul_f32 v[110:111], v[110:111], s[80:81] op_sel_hi:[1,0]
	v_pk_mul_f32 v[108:109], v[108:109], s[80:81] op_sel_hi:[1,0]
	v_pk_fma_f32 v[118:119], v[98:99], v[156:157], v[110:111]
	v_pk_fma_f32 v[116:117], v[96:97], v[158:159], v[108:109]
	s_waitcnt lgkmcnt(8)
	v_pk_mul_f32 v[96:97], v[122:123], s[80:81] op_sel_hi:[1,0]
	v_pk_mul_f32 v[98:99], v[120:121], s[80:81] op_sel_hi:[1,0]
	v_pk_fma_f32 v[122:123], v[94:95], v[166:167], v[96:97]
	v_pk_fma_f32 v[120:121], v[92:93], v[168:169], v[98:99]
	s_waitcnt lgkmcnt(5)
	v_pk_mul_f32 v[92:93], v[202:203], s[80:81] op_sel_hi:[1,0]
	v_pk_mul_f32 v[94:95], v[200:201], s[80:81] op_sel_hi:[1,0]
	ds_write_b128 v184, v[226:229]
	ds_write_b128 v184, v[234:237] offset:1152
	v_pk_fma_f32 v[98:99], v[90:91], v[170:171], v[92:93]
	v_pk_fma_f32 v[96:97], v[88:89], v[172:173], v[94:95]
	ds_read_b128 v[88:91], v182
	ds_read_b128 v[92:95], v182 offset:64
	s_waitcnt lgkmcnt(8)
	v_pk_mul_f32 v[108:109], v[206:207], s[80:81] op_sel_hi:[1,0]
	v_pk_mul_f32 v[200:201], v[204:205], s[80:81] op_sel_hi:[1,0]
	v_pk_fma_f32 v[110:111], v[74:75], v[174:175], v[108:109]
	v_pk_fma_f32 v[108:109], v[72:73], v[176:177], v[200:201]
	s_waitcnt lgkmcnt(5)
	v_pk_mul_f32 v[72:73], v[216:217], s[80:81] op_sel_hi:[1,0]
	v_pk_mul_f32 v[74:75], v[214:215], s[80:81] op_sel_hi:[1,0]
	v_pk_fma_f32 v[82:83], v[82:83], v[156:157], v[72:73]
	v_pk_fma_f32 v[80:81], v[80:81], v[158:159], v[74:75]
	s_waitcnt lgkmcnt(4)
	v_pk_mul_f32 v[72:73], v[220:221], s[80:81] op_sel_hi:[1,0]
	v_pk_mul_f32 v[74:75], v[218:219], s[80:81] op_sel_hi:[1,0]
	v_pk_fma_f32 v[86:87], v[86:87], v[166:167], v[72:73]
	v_pk_fma_f32 v[84:85], v[84:85], v[168:169], v[74:75]
	s_waitcnt lgkmcnt(1)
	v_pk_mul_f32 v[72:73], v[90:91], s[80:81] op_sel_hi:[1,0]
	v_pk_mul_f32 v[74:75], v[88:89], s[80:81] op_sel_hi:[1,0]
	v_pk_fma_f32 v[70:71], v[70:71], v[170:171], v[72:73]
	s_waitcnt lgkmcnt(0)
	v_pk_mul_f32 v[72:73], v[94:95], s[80:81] op_sel_hi:[1,0]
	v_pk_mul_f32 v[88:89], v[92:93], s[80:81] op_sel_hi:[1,0]
	v_pk_fma_f32 v[68:69], v[68:69], v[172:173], v[74:75]
	v_pk_fma_f32 v[74:75], v[66:67], v[174:175], v[72:73]
	v_pk_fma_f32 v[72:73], v[64:65], v[176:177], v[88:89]
	v_readlane_b32 s6, v255, 0
	v_lshl_add_u64 v[64:65], v[178:179], 0, s[70:71]
	v_readlane_b32 s7, v255, 1
	global_load_dwordx4 v[88:91], v[64:65], off nt
	global_load_dwordx4 v[92:95], v[64:65], off offset:512 nt
	v_lshl_add_u64 v[64:65], v[178:179], 0, s[6:7]
	v_readlane_b32 s6, v255, 2
	global_load_dwordx4 v[200:203], v[64:65], off nt
	global_load_dwordx4 v[204:207], v[64:65], off offset:512 nt
	v_lshl_add_u64 v[64:65], v[178:179], 0, s[14:15]
	v_readlane_b32 s7, v255, 3
	global_load_dwordx4 v[214:217], v[64:65], off nt
	global_load_dwordx4 v[218:221], v[64:65], off offset:512 nt
	v_lshl_add_u64 v[64:65], v[178:179], 0, s[6:7]
	global_load_dwordx4 v[222:225], v[64:65], off nt
	global_load_dwordx4 v[226:229], v[64:65], off offset:512 nt
	s_waitcnt vmcnt(15)
	ds_write_b128 v184, v[100:103]
	s_waitcnt vmcnt(13)
	ds_write_b128 v184, v[112:115] offset:1152
	ds_read_b128 v[64:67], v182
	ds_read_b128 v[100:103], v182 offset:64
	ds_write_b128 v184, v[104:107]
	s_waitcnt vmcnt(12)
	ds_write_b128 v184, v[192:195] offset:1152
	ds_read_b128 v[104:107], v182
	ds_read_b128 v[112:115], v182 offset:64
	s_waitcnt vmcnt(11)
	ds_write_b128 v184, v[196:199]
	s_waitcnt vmcnt(9)
	ds_write_b128 v184, v[250:253] offset:1152
	ds_read_b128 v[192:195], v182
	ds_read_b128 v[196:199], v182 offset:64
	s_waitcnt lgkmcnt(9)
	v_pk_mul_f32 v[64:65], v[64:65], s[80:81] op_sel_hi:[1,0]
	v_pk_mul_f32 v[66:67], v[66:67], s[80:81] op_sel_hi:[1,0]
	v_pk_fma_f32 v[60:61], v[60:61], v[158:159], v[64:65]
	s_waitcnt lgkmcnt(8)
	v_pk_mul_f32 v[64:65], v[102:103], s[80:81] op_sel_hi:[1,0]
	v_pk_mul_f32 v[100:101], v[100:101], s[80:81] op_sel_hi:[1,0]
	v_pk_fma_f32 v[62:63], v[62:63], v[156:157], v[66:67]
	v_pk_fma_f32 v[66:67], v[58:59], v[166:167], v[64:65]
	v_pk_fma_f32 v[64:65], v[56:57], v[168:169], v[100:101]
	ds_write_b128 v184, v[238:241]
	s_waitcnt vmcnt(8)
	ds_write_b128 v184, v[208:211] offset:1152
	s_waitcnt lgkmcnt(7)
	v_pk_mul_f32 v[56:57], v[106:107], s[80:81] op_sel_hi:[1,0]
	v_pk_mul_f32 v[58:59], v[104:105], s[80:81] op_sel_hi:[1,0]
	ds_read_b128 v[100:103], v182
	ds_read_b128 v[104:107], v182 offset:64
	v_pk_fma_f32 v[54:55], v[54:55], v[170:171], v[56:57]
	s_waitcnt lgkmcnt(8)
	v_pk_mul_f32 v[56:57], v[114:115], s[80:81] op_sel_hi:[1,0]
	v_pk_mul_f32 v[112:113], v[112:113], s[80:81] op_sel_hi:[1,0]
	v_pk_fma_f32 v[52:53], v[52:53], v[172:173], v[58:59]
	v_pk_fma_f32 v[58:59], v[42:43], v[174:175], v[56:57]
	v_pk_fma_f32 v[56:57], v[40:41], v[176:177], v[112:113]
	s_waitcnt lgkmcnt(5)
	v_pk_mul_f32 v[40:41], v[194:195], s[80:81] op_sel_hi:[1,0]
	v_pk_mul_f32 v[42:43], v[192:193], s[80:81] op_sel_hi:[1,0]
	v_pk_fma_f32 v[46:47], v[46:47], v[156:157], v[40:41]
	v_pk_fma_f32 v[44:45], v[44:45], v[158:159], v[42:43]
	s_waitcnt lgkmcnt(4)
	v_pk_mul_f32 v[40:41], v[198:199], s[80:81] op_sel_hi:[1,0]
	v_pk_mul_f32 v[42:43], v[196:197], s[80:81] op_sel_hi:[1,0]
	v_pk_fma_f32 v[50:51], v[50:51], v[166:167], v[40:41]
	v_pk_fma_f32 v[48:49], v[48:49], v[168:169], v[42:43]
	s_waitcnt lgkmcnt(1)
	v_pk_mul_f32 v[40:41], v[102:103], s[80:81] op_sel_hi:[1,0]
	v_pk_mul_f32 v[42:43], v[100:101], s[80:81] op_sel_hi:[1,0]
	v_pk_fma_f32 v[38:39], v[38:39], v[170:171], v[40:41]
	s_waitcnt lgkmcnt(0)
	v_pk_mul_f32 v[40:41], v[106:107], s[80:81] op_sel_hi:[1,0]
	v_pk_mul_f32 v[100:101], v[104:105], s[80:81] op_sel_hi:[1,0]
	v_pk_fma_f32 v[36:37], v[36:37], v[172:173], v[42:43]
	v_pk_fma_f32 v[42:43], v[34:35], v[174:175], v[40:41]
	v_pk_fma_f32 v[40:41], v[32:33], v[176:177], v[100:101]
	s_nop 0
	s_waitcnt vmcnt(7)
	ds_write_b128 v184, v[88:91]
	s_waitcnt vmcnt(5)
	ds_write_b128 v184, v[200:203] offset:1152
	ds_read_b128 v[32:35], v182
	ds_read_b128 v[88:91], v182 offset:64
	ds_write_b128 v184, v[92:95]
	s_waitcnt vmcnt(4)
	ds_write_b128 v184, v[204:207] offset:1152
	ds_read_b128 v[92:95], v182
	ds_read_b128 v[100:103], v182 offset:64
	s_waitcnt vmcnt(3)
	ds_write_b128 v184, v[214:217]
	s_waitcnt vmcnt(1)
	ds_write_b128 v184, v[222:225] offset:1152
	ds_read_b128 v[104:107], v182
	ds_read_b128 v[112:115], v182 offset:64
	s_waitcnt lgkmcnt(9)
	v_pk_mul_f32 v[32:33], v[32:33], s[80:81] op_sel_hi:[1,0]
	v_pk_mul_f32 v[34:35], v[34:35], s[80:81] op_sel_hi:[1,0]
	v_pk_fma_f32 v[28:29], v[28:29], v[158:159], v[32:33]
	s_waitcnt lgkmcnt(8)
	v_pk_mul_f32 v[32:33], v[90:91], s[80:81] op_sel_hi:[1,0]
	v_pk_mul_f32 v[88:89], v[88:89], s[80:81] op_sel_hi:[1,0]
	v_pk_fma_f32 v[30:31], v[30:31], v[156:157], v[34:35]
	v_pk_fma_f32 v[34:35], v[26:27], v[166:167], v[32:33]
	v_pk_fma_f32 v[32:33], v[24:25], v[168:169], v[88:89]
	ds_write_b128 v184, v[218:221]
	s_waitcnt vmcnt(0)
	ds_write_b128 v184, v[226:229] offset:1152
	s_waitcnt lgkmcnt(7)
	v_pk_mul_f32 v[24:25], v[94:95], s[80:81] op_sel_hi:[1,0]
	v_pk_mul_f32 v[26:27], v[92:93], s[80:81] op_sel_hi:[1,0]
	ds_read_b128 v[88:91], v182
	ds_read_b128 v[92:95], v182 offset:64
	v_pk_fma_f32 v[22:23], v[22:23], v[170:171], v[24:25]
	s_waitcnt lgkmcnt(8)
	v_pk_mul_f32 v[24:25], v[102:103], s[80:81] op_sel_hi:[1,0]
	v_pk_mul_f32 v[100:101], v[100:101], s[80:81] op_sel_hi:[1,0]
	v_pk_fma_f32 v[20:21], v[20:21], v[172:173], v[26:27]
	v_pk_fma_f32 v[26:27], v[14:15], v[174:175], v[24:25]
	v_pk_fma_f32 v[24:25], v[12:13], v[176:177], v[100:101]
	s_waitcnt lgkmcnt(5)
	v_pk_mul_f32 v[12:13], v[106:107], s[80:81] op_sel_hi:[1,0]
	v_pk_mul_f32 v[100:101], v[104:105], s[80:81] op_sel_hi:[1,0]
	v_pk_fma_f32 v[14:15], v[78:79], v[156:157], v[12:13]
	v_pk_fma_f32 v[12:13], v[76:77], v[158:159], v[100:101]
	s_waitcnt lgkmcnt(4)
	v_pk_mul_f32 v[76:77], v[114:115], s[80:81] op_sel_hi:[1,0]
	v_pk_mul_f32 v[78:79], v[112:113], s[80:81] op_sel_hi:[1,0]
	v_pk_fma_f32 v[18:19], v[18:19], v[166:167], v[76:77]
	v_pk_fma_f32 v[16:17], v[16:17], v[168:169], v[78:79]
	s_waitcnt lgkmcnt(1)
	v_pk_mul_f32 v[76:77], v[90:91], s[80:81] op_sel_hi:[1,0]
	v_pk_mul_f32 v[78:79], v[88:89], s[80:81] op_sel_hi:[1,0]
	v_pk_fma_f32 v[6:7], v[6:7], v[170:171], v[76:77]
	s_waitcnt lgkmcnt(0)
	v_pk_mul_f32 v[76:77], v[94:95], s[80:81] op_sel_hi:[1,0]
	v_pk_fma_f32 v[4:5], v[4:5], v[172:173], v[78:79]
	v_pk_mul_f32 v[78:79], v[92:93], s[80:81] op_sel_hi:[1,0]
	v_pk_fma_f32 v[10:11], v[10:11], v[174:175], v[76:77]
	v_add_f32_e32 v76, v140, v141
	v_add_f32_e32 v77, v142, v143
	v_pk_fma_f32 v[8:9], v[8:9], v[176:177], v[78:79]
	v_add_f32_e32 v76, v76, v77
	v_mul_f32_e32 v77, v141, v141
	v_mul_f32_e32 v78, v143, v143
	v_fmac_f32_e32 v77, v140, v140
	v_fmac_f32_e32 v78, v142, v142
	v_add_f32_e32 v77, v77, v78
	v_add_f32_e32 v78, v144, v145
	v_add_f32_e32 v79, v146, v147
	v_add_f32_e32 v76, 0, v76
	v_add_f32_e32 v78, v78, v79
	v_add_f32_e32 v76, v78, v76
	v_mul_f32_e32 v78, v145, v145
	v_mul_f32_e32 v79, v147, v147
	v_fmac_f32_e32 v78, v144, v144
	v_fmac_f32_e32 v79, v146, v146
	v_add_f32_e32 v78, v78, v79
	v_add_f32_e32 v77, v77, v78
	v_add_f32_e32 v78, v148, v149
	v_add_f32_e32 v79, v150, v151
	v_add_f32_e32 v78, v78, v79
	v_add_f32_e32 v76, v78, v76
	v_mul_f32_e32 v78, v149, v149
	v_mul_f32_e32 v79, v151, v151
	v_fmac_f32_e32 v78, v148, v148
	v_fmac_f32_e32 v79, v150, v150
	v_add_f32_e32 v78, v78, v79
	v_add_f32_e32 v77, v78, v77
	v_add_f32_e32 v78, v152, v153
	v_add_f32_e32 v79, v154, v155
	v_add_f32_e32 v78, v78, v79
	v_add_f32_e32 v76, v78, v76
	v_mul_f32_e32 v78, v153, v153
	v_mul_f32_e32 v79, v155, v155
	v_fmac_f32_e32 v78, v152, v152
	v_fmac_f32_e32 v79, v154, v154
	v_add_f32_e32 v78, v78, v79
	v_add_f32_e32 v77, v78, v77
	v_mov_b32_e32 v78, v76
	v_mov_b32_e32 v79, v77
	s_nop 0
	v_permlane16_swap_b32_e32 v76, v78
	v_permlane16_swap_b32_e32 v77, v79
	v_add_f32_e32 v76, v76, v78
	v_add_f32_e32 v77, v77, v79
	v_mov_b32_e32 v78, v76
	v_mov_b32_e32 v79, v77
	s_nop 0
	v_permlane32_swap_b32_e32 v76, v78
	v_permlane32_swap_b32_e32 v77, v79
	s_and_saveexec_b64 s[6:7], s[8:9]
	v_pk_add_f32 v[76:77], v[76:77], v[78:79]
	ds_write_b64 v190, v[76:77]
	s_or_b64 exec, exec, s[6:7]
	v_add_f32_e32 v76, v132, v133
	v_add_f32_e32 v77, v134, v135
	v_add_f32_e32 v76, v76, v77
	v_mul_f32_e32 v77, v133, v133
	v_mul_f32_e32 v78, v135, v135
	v_fmac_f32_e32 v77, v132, v132
	v_fmac_f32_e32 v78, v134, v134
	v_add_f32_e32 v77, v77, v78
	v_add_f32_e32 v78, v136, v137
	v_add_f32_e32 v79, v138, v139
	v_add_f32_e32 v76, 0, v76
	v_add_f32_e32 v78, v78, v79
	v_add_f32_e32 v76, v78, v76
	v_mul_f32_e32 v78, v137, v137
	v_mul_f32_e32 v79, v139, v139
	v_fmac_f32_e32 v78, v136, v136
	v_fmac_f32_e32 v79, v138, v138
	v_add_f32_e32 v78, v78, v79
	v_add_f32_e32 v77, v77, v78
	v_add_f32_e32 v78, v124, v125
	v_add_f32_e32 v79, v126, v127
	v_add_f32_e32 v78, v78, v79
	v_add_f32_e32 v76, v78, v76
	v_mul_f32_e32 v78, v125, v125
	v_mul_f32_e32 v79, v127, v127
	v_fmac_f32_e32 v78, v124, v124
	v_fmac_f32_e32 v79, v126, v126
	v_add_f32_e32 v78, v78, v79
	v_add_f32_e32 v77, v78, v77
	v_add_f32_e32 v78, v128, v129
	v_add_f32_e32 v79, v130, v131
	v_add_f32_e32 v78, v78, v79
	v_add_f32_e32 v76, v78, v76
	v_mul_f32_e32 v78, v129, v129
	v_mul_f32_e32 v79, v131, v131
	v_fmac_f32_e32 v78, v128, v128
	v_fmac_f32_e32 v79, v130, v130
	v_add_f32_e32 v78, v78, v79
	v_add_f32_e32 v77, v78, v77
	v_mov_b32_e32 v78, v76
	v_mov_b32_e32 v79, v77
	s_nop 0
	v_permlane16_swap_b32_e32 v76, v78
	v_permlane16_swap_b32_e32 v77, v79
	v_add_f32_e32 v76, v76, v78
	v_add_f32_e32 v77, v77, v79
	v_mov_b32_e32 v78, v76
	v_mov_b32_e32 v79, v77
	s_nop 0
	v_permlane32_swap_b32_e32 v76, v78
	v_permlane32_swap_b32_e32 v77, v79
	s_and_saveexec_b64 s[6:7], s[8:9]
	v_pk_add_f32 v[76:77], v[76:77], v[78:79]
	ds_write_b64 v190, v[76:77] offset:512
	s_or_b64 exec, exec, s[6:7]
	v_add_f32_e32 v76, v116, v117
	v_add_f32_e32 v77, v118, v119
	v_add_f32_e32 v76, v76, v77
	v_mul_f32_e32 v77, v117, v117
	v_mul_f32_e32 v78, v119, v119
	v_fmac_f32_e32 v77, v116, v116
	v_fmac_f32_e32 v78, v118, v118
	v_add_f32_e32 v77, v77, v78
	v_add_f32_e32 v78, v120, v121
	v_add_f32_e32 v79, v122, v123
	v_add_f32_e32 v76, 0, v76
	v_add_f32_e32 v78, v78, v79
	v_add_f32_e32 v76, v78, v76
	v_mul_f32_e32 v78, v121, v121
	v_mul_f32_e32 v79, v123, v123
	v_fmac_f32_e32 v78, v120, v120
	v_fmac_f32_e32 v79, v122, v122
	v_add_f32_e32 v78, v78, v79
	v_add_f32_e32 v77, v77, v78
	v_add_f32_e32 v78, v96, v97
	v_add_f32_e32 v79, v98, v99
	v_add_f32_e32 v78, v78, v79
	v_add_f32_e32 v76, v78, v76
	v_mul_f32_e32 v78, v97, v97
	v_mul_f32_e32 v79, v99, v99
	v_fmac_f32_e32 v78, v96, v96
	v_fmac_f32_e32 v79, v98, v98
	v_add_f32_e32 v78, v78, v79
	v_add_f32_e32 v77, v78, v77
	v_add_f32_e32 v78, v108, v109
	v_add_f32_e32 v79, v110, v111
	v_add_f32_e32 v78, v78, v79
	v_add_f32_e32 v76, v78, v76
	v_mul_f32_e32 v78, v109, v109
	v_mul_f32_e32 v79, v111, v111
	v_fmac_f32_e32 v78, v108, v108
	v_fmac_f32_e32 v79, v110, v110
	v_add_f32_e32 v78, v78, v79
	v_add_f32_e32 v77, v78, v77
	v_mov_b32_e32 v78, v76
	v_mov_b32_e32 v79, v77
	s_nop 0
	v_permlane16_swap_b32_e32 v76, v78
	v_permlane16_swap_b32_e32 v77, v79
	v_add_f32_e32 v76, v76, v78
	v_add_f32_e32 v77, v77, v79
	v_mov_b32_e32 v78, v76
	v_mov_b32_e32 v79, v77
	s_nop 0
	v_permlane32_swap_b32_e32 v76, v78
	v_permlane32_swap_b32_e32 v77, v79
	s_and_saveexec_b64 s[6:7], s[8:9]
	v_pk_add_f32 v[76:77], v[76:77], v[78:79]
	ds_write_b64 v190, v[76:77] offset:1024
	s_or_b64 exec, exec, s[6:7]
	v_add_f32_e32 v76, v80, v81
	v_add_f32_e32 v77, v82, v83
	v_add_f32_e32 v76, v76, v77
	v_mul_f32_e32 v77, v81, v81
	v_mul_f32_e32 v78, v83, v83
	v_fmac_f32_e32 v77, v80, v80
	v_fmac_f32_e32 v78, v82, v82
	v_add_f32_e32 v77, v77, v78
	v_add_f32_e32 v78, v84, v85
	v_add_f32_e32 v79, v86, v87
	v_add_f32_e32 v76, 0, v76
	v_add_f32_e32 v78, v78, v79
	v_add_f32_e32 v76, v78, v76
	v_mul_f32_e32 v78, v85, v85
	v_mul_f32_e32 v79, v87, v87
	v_fmac_f32_e32 v78, v84, v84
	v_fmac_f32_e32 v79, v86, v86
	v_add_f32_e32 v78, v78, v79
	v_add_f32_e32 v77, v77, v78
	v_add_f32_e32 v78, v68, v69
	v_add_f32_e32 v79, v70, v71
	v_add_f32_e32 v78, v78, v79
	v_add_f32_e32 v76, v78, v76
	v_mul_f32_e32 v78, v69, v69
	v_mul_f32_e32 v79, v71, v71
	v_fmac_f32_e32 v78, v68, v68
	v_fmac_f32_e32 v79, v70, v70
	v_add_f32_e32 v78, v78, v79
	v_add_f32_e32 v77, v78, v77
	v_add_f32_e32 v78, v72, v73
	v_add_f32_e32 v79, v74, v75
	v_add_f32_e32 v78, v78, v79
	v_add_f32_e32 v76, v78, v76
	v_mul_f32_e32 v78, v73, v73
	v_mul_f32_e32 v79, v75, v75
	v_fmac_f32_e32 v78, v72, v72
	v_fmac_f32_e32 v79, v74, v74
	v_add_f32_e32 v78, v78, v79
	v_add_f32_e32 v77, v78, v77
	v_mov_b32_e32 v78, v76
	v_mov_b32_e32 v79, v77
	s_nop 0
	v_permlane16_swap_b32_e32 v76, v78
	v_permlane16_swap_b32_e32 v77, v79
	v_add_f32_e32 v76, v76, v78
	v_add_f32_e32 v77, v77, v79
	v_mov_b32_e32 v78, v76
	v_mov_b32_e32 v79, v77
	s_nop 0
	v_permlane32_swap_b32_e32 v76, v78
	v_permlane32_swap_b32_e32 v77, v79
	s_and_saveexec_b64 s[6:7], s[8:9]
	v_pk_add_f32 v[76:77], v[76:77], v[78:79]
	ds_write_b64 v190, v[76:77] offset:1536
	s_or_b64 exec, exec, s[6:7]
	v_add_f32_e32 v76, v60, v61
	v_add_f32_e32 v77, v62, v63
	v_add_f32_e32 v76, v76, v77
	v_mul_f32_e32 v77, v61, v61
	v_mul_f32_e32 v78, v63, v63
	v_fmac_f32_e32 v77, v60, v60
	v_fmac_f32_e32 v78, v62, v62
	v_add_f32_e32 v77, v77, v78
	v_add_f32_e32 v78, v64, v65
	v_add_f32_e32 v79, v66, v67
	v_add_f32_e32 v76, 0, v76
	v_add_f32_e32 v78, v78, v79
	v_add_f32_e32 v76, v78, v76
	v_mul_f32_e32 v78, v65, v65
	v_mul_f32_e32 v79, v67, v67
	v_fmac_f32_e32 v78, v64, v64
	v_fmac_f32_e32 v79, v66, v66
	v_add_f32_e32 v78, v78, v79
	v_add_f32_e32 v77, v77, v78
	v_add_f32_e32 v78, v52, v53
	v_add_f32_e32 v79, v54, v55
	v_add_f32_e32 v78, v78, v79
	v_add_f32_e32 v76, v78, v76
	v_mul_f32_e32 v78, v53, v53
	v_mul_f32_e32 v79, v55, v55
	v_fmac_f32_e32 v78, v52, v52
	v_fmac_f32_e32 v79, v54, v54
	v_add_f32_e32 v78, v78, v79
	v_add_f32_e32 v77, v78, v77
	v_add_f32_e32 v78, v56, v57
	v_add_f32_e32 v79, v58, v59
	v_add_f32_e32 v78, v78, v79
	v_add_f32_e32 v76, v78, v76
	v_mul_f32_e32 v78, v57, v57
	v_mul_f32_e32 v79, v59, v59
	v_fmac_f32_e32 v78, v56, v56
	v_fmac_f32_e32 v79, v58, v58
	v_add_f32_e32 v78, v78, v79
	v_add_f32_e32 v77, v78, v77
	v_mov_b32_e32 v78, v76
	v_mov_b32_e32 v79, v77
	s_nop 0
	v_permlane16_swap_b32_e32 v76, v78
	v_permlane16_swap_b32_e32 v77, v79
	v_add_f32_e32 v76, v76, v78
	v_add_f32_e32 v77, v77, v79
	v_mov_b32_e32 v78, v76
	v_mov_b32_e32 v79, v77
	s_nop 0
	v_permlane32_swap_b32_e32 v76, v78
	v_permlane32_swap_b32_e32 v77, v79
	s_and_saveexec_b64 s[6:7], s[8:9]
	v_pk_add_f32 v[76:77], v[76:77], v[78:79]
	ds_write_b64 v190, v[76:77] offset:4096
	s_or_b64 exec, exec, s[6:7]
	v_add_f32_e32 v76, v44, v45
	v_add_f32_e32 v77, v46, v47
	v_add_f32_e32 v76, v76, v77
	v_mul_f32_e32 v77, v45, v45
	v_mul_f32_e32 v78, v47, v47
	v_fmac_f32_e32 v77, v44, v44
	v_fmac_f32_e32 v78, v46, v46
	v_add_f32_e32 v77, v77, v78
	v_add_f32_e32 v78, v48, v49
	v_add_f32_e32 v79, v50, v51
	v_add_f32_e32 v76, 0, v76
	v_add_f32_e32 v78, v78, v79
	v_add_f32_e32 v76, v78, v76
	v_mul_f32_e32 v78, v49, v49
	v_mul_f32_e32 v79, v51, v51
	v_fmac_f32_e32 v78, v48, v48
	v_fmac_f32_e32 v79, v50, v50
	v_add_f32_e32 v78, v78, v79
	v_add_f32_e32 v77, v77, v78
	v_add_f32_e32 v78, v36, v37
	v_add_f32_e32 v79, v38, v39
	v_add_f32_e32 v78, v78, v79
	v_add_f32_e32 v76, v78, v76
	v_mul_f32_e32 v78, v37, v37
	v_mul_f32_e32 v79, v39, v39
	v_fmac_f32_e32 v78, v36, v36
	v_fmac_f32_e32 v79, v38, v38
	v_add_f32_e32 v78, v78, v79
	v_add_f32_e32 v77, v78, v77
	v_add_f32_e32 v78, v40, v41
	v_add_f32_e32 v79, v42, v43
	v_add_f32_e32 v78, v78, v79
	v_add_f32_e32 v76, v78, v76
	v_mul_f32_e32 v78, v41, v41
	v_mul_f32_e32 v79, v43, v43
	v_fmac_f32_e32 v78, v40, v40
	v_fmac_f32_e32 v79, v42, v42
	v_add_f32_e32 v78, v78, v79
	v_add_f32_e32 v77, v78, v77
	v_mov_b32_e32 v78, v76
	v_mov_b32_e32 v79, v77
	s_nop 0
	v_permlane16_swap_b32_e32 v76, v78
	v_permlane16_swap_b32_e32 v77, v79
	v_add_f32_e32 v76, v76, v78
	v_add_f32_e32 v77, v77, v79
	v_mov_b32_e32 v78, v76
	v_mov_b32_e32 v79, v77
	s_nop 0
	v_permlane32_swap_b32_e32 v76, v78
	v_permlane32_swap_b32_e32 v77, v79
	s_and_saveexec_b64 s[6:7], s[8:9]
	v_pk_add_f32 v[76:77], v[76:77], v[78:79]
	ds_write_b64 v190, v[76:77] offset:4608
	s_or_b64 exec, exec, s[6:7]
	v_add_f32_e32 v76, v28, v29
	v_add_f32_e32 v77, v30, v31
	v_add_f32_e32 v76, v76, v77
	v_mul_f32_e32 v77, v29, v29
	v_mul_f32_e32 v78, v31, v31
	v_fmac_f32_e32 v77, v28, v28
	v_fmac_f32_e32 v78, v30, v30
	v_add_f32_e32 v77, v77, v78
	v_add_f32_e32 v78, v32, v33
	v_add_f32_e32 v79, v34, v35
	v_add_f32_e32 v76, 0, v76
	v_add_f32_e32 v78, v78, v79
	v_add_f32_e32 v76, v78, v76
	v_mul_f32_e32 v78, v33, v33
	v_mul_f32_e32 v79, v35, v35
	v_fmac_f32_e32 v78, v32, v32
	v_fmac_f32_e32 v79, v34, v34
	v_add_f32_e32 v78, v78, v79
	v_add_f32_e32 v77, v77, v78
	v_add_f32_e32 v78, v20, v21
	v_add_f32_e32 v79, v22, v23
	v_add_f32_e32 v78, v78, v79
	v_add_f32_e32 v76, v78, v76
	v_mul_f32_e32 v78, v21, v21
	v_mul_f32_e32 v79, v23, v23
	v_fmac_f32_e32 v78, v20, v20
	v_fmac_f32_e32 v79, v22, v22
	v_add_f32_e32 v78, v78, v79
	v_add_f32_e32 v77, v78, v77
	v_add_f32_e32 v78, v24, v25
	v_add_f32_e32 v79, v26, v27
	v_add_f32_e32 v78, v78, v79
	v_add_f32_e32 v76, v78, v76
	v_mul_f32_e32 v78, v25, v25
	v_mul_f32_e32 v79, v27, v27
	v_fmac_f32_e32 v78, v24, v24
	v_fmac_f32_e32 v79, v26, v26
	v_add_f32_e32 v78, v78, v79
	v_add_f32_e32 v77, v78, v77
	v_mov_b32_e32 v78, v76
	v_mov_b32_e32 v79, v77
	s_nop 0
	v_permlane16_swap_b32_e32 v76, v78
	v_permlane16_swap_b32_e32 v77, v79
	v_add_f32_e32 v76, v76, v78
	v_add_f32_e32 v77, v77, v79
	v_mov_b32_e32 v78, v76
	v_mov_b32_e32 v79, v77
	s_nop 0
	v_permlane32_swap_b32_e32 v76, v78
	v_permlane32_swap_b32_e32 v77, v79
	s_and_saveexec_b64 s[6:7], s[8:9]
	v_pk_add_f32 v[76:77], v[76:77], v[78:79]
	ds_write_b64 v190, v[76:77] offset:5120
	s_or_b64 exec, exec, s[6:7]
	v_add_f32_e32 v76, v12, v13
	v_add_f32_e32 v77, v14, v15
	v_add_f32_e32 v76, v76, v77
	v_mul_f32_e32 v77, v13, v13
	v_mul_f32_e32 v78, v15, v15
	v_fmac_f32_e32 v77, v12, v12
	v_fmac_f32_e32 v78, v14, v14
	v_add_f32_e32 v77, v77, v78
	v_add_f32_e32 v78, v16, v17
	v_add_f32_e32 v79, v18, v19
	v_add_f32_e32 v76, 0, v76
	v_add_f32_e32 v78, v78, v79
	v_add_f32_e32 v76, v78, v76
	v_mul_f32_e32 v78, v17, v17
	v_mul_f32_e32 v79, v19, v19
	v_fmac_f32_e32 v78, v16, v16
	v_fmac_f32_e32 v79, v18, v18
	v_add_f32_e32 v78, v78, v79
	v_add_f32_e32 v77, v77, v78
	v_add_f32_e32 v78, v4, v5
	v_add_f32_e32 v79, v6, v7
	v_add_f32_e32 v78, v78, v79
	v_add_f32_e32 v76, v78, v76
	v_mul_f32_e32 v78, v5, v5
	v_mul_f32_e32 v79, v7, v7
	v_fmac_f32_e32 v78, v4, v4
	v_fmac_f32_e32 v79, v6, v6
	v_add_f32_e32 v78, v78, v79
	v_add_f32_e32 v77, v78, v77
	v_add_f32_e32 v78, v8, v9
	v_add_f32_e32 v79, v10, v11
	v_add_f32_e32 v78, v78, v79
	v_add_f32_e32 v76, v78, v76
	v_mul_f32_e32 v78, v9, v9
	v_mul_f32_e32 v79, v11, v11
	v_fmac_f32_e32 v78, v8, v8
	v_fmac_f32_e32 v79, v10, v10
	v_add_f32_e32 v78, v78, v79
	v_add_f32_e32 v77, v78, v77
	v_mov_b32_e32 v78, v76
	v_mov_b32_e32 v79, v77
	s_nop 0
	v_permlane16_swap_b32_e32 v76, v78
	v_permlane16_swap_b32_e32 v77, v79
	v_add_f32_e32 v76, v76, v78
	v_add_f32_e32 v77, v77, v79
	v_mov_b32_e32 v78, v76
	v_mov_b32_e32 v79, v77
	s_nop 0
	v_permlane32_swap_b32_e32 v76, v78
	v_permlane32_swap_b32_e32 v77, v79
	s_and_saveexec_b64 s[6:7], s[8:9]
	v_pk_add_f32 v[76:77], v[76:77], v[78:79]
	ds_write_b64 v190, v[76:77] offset:5632
	s_or_b64 exec, exec, s[6:7]
	s_waitcnt lgkmcnt(0)
	s_barrier
	s_add_u32 s56, s26, 0x1ac00000
	v_add_u32_e32 v156, s68, v186
	s_addc_u32 s57, s27, 0
	v_ashrrev_i32_e32 v157, 31, v156
	s_and_saveexec_b64 s[6:7], s[10:11]
	s_cbranch_execz .LBB0_835
	ds_read_b128 v[76:79], v189
	ds_read_b128 v[88:91], v189 offset:16
	s_ashr_i32 s83, s82, 31
	s_waitcnt lgkmcnt(1)
	v_mov_b32_e32 v92, v76
	s_waitcnt lgkmcnt(0)
	v_mov_b32_e32 v93, v88
	v_mov_b32_e32 v94, v78
	v_mov_b32_e32 v95, v90
	v_pk_add_f32 v[92:93], v[92:93], v[94:95]
	v_mov_b32_e32 v88, v77
	v_mov_b32_e32 v90, v79
	v_add_f32_e32 v78, v92, v93
	v_pk_add_f32 v[76:77], v[88:89], v[90:91]
	s_nop 0
	v_add_f32_e32 v77, v76, v77
	v_mul_f32_e32 v76, 0x3b800000, v78
	v_fma_f32 v77, -v78, v76, v77
	v_lshlrev_b64 v[78:79], 6, v[156:157]
	v_lshl_add_u64 v[78:79], s[56:57], 0, v[78:79]
	v_max_f32_e32 v77, 0, v77
	v_lshl_add_u64 v[78:79], s[82:83], 3, v[78:79]
	global_store_dwordx2 v[78:79], v[76:77], off sc1
